# NSA selected branch: (s-m)*c+8 folded into one packed FMA with a per-step constant, dead zero-inits before fp8 cvt pairs removed; DA V^T LDS layout permuted so PV A-fragments are single b128 reads
# speedup vs baseline: 1.0653x; 1.0124x over previous
; #define LAS __attribute__((address_space(3)))
; __device__ __forceinline__ void phase_da(const Params& p, int layer, LAS unsigned char* lds, const bf16_t* Z, bf16_t* Mixed, int tid, int wid, int lane) {
;     LAS bf16_t* Ks0 = (LAS bf16_t*)lds;
;     const int r = lane & 31, h = lane >> 5;
;     const float lam_init = 0.8f - 0.6f * expf(-0.3f * (float)layer);
;     float lam;
;     { const float* lf = p.da_lambda + layer * 128; float s1 = 0.f, s2 = 0.f;
;       for (int i = 0; i < 32; ++i) { s1 += lf[i] * lf[32 + i]; s2 += lf[64 + i] * lf[96 + i]; }
;       lam = expf(s1) - expf(s2) + lam_init; }
;     const float c = 0.17677669529663687f * LOG2E;
.LBB0_229:
	v_cvt_f32_u32_e32 v0, s80
	s_mov_b32 s2, 0xc2ce8ed0
	s_mov_b64 s[8:9], s[0:1]
	v_readlane_b32 s10, v254, 0
	v_mul_f32_e32 v0, 0xbe99999a, v0
	v_cmp_ngt_f32_e32 vcc, s2, v0
	s_mov_b32 s2, 0x42b17218
	s_mov_b32 s11, s86
	v_mov_b32_e32 v66, v187
	s_barrier
	v_cmp_nlt_f32_e64 s[2:3], s2, v0
	s_barrier
	s_cmpk_gt_i32 s10, 0xff
	v_readfirstlane_b32 s12, v66
	s_cbranch_scc1 .LBB0_275
	v_mul_f32_e32 v2, 0x3fb8aa3b, v0
	s_mov_b32 s13, 0x3fb8aa3b
	v_fma_f32 v3, v0, s13, -v2
	v_fmac_f32_e32 v3, 0x32a5705f, v0
	v_rndne_f32_e32 v0, v2
	v_sub_f32_e32 v2, v2, v0
	v_add_f32_e32 v2, v2, v3
	v_exp_f32_e32 v2, v2
	v_cvt_i32_f32_e32 v0, v0
	s_load_dwordx4 s[4:7], s[8:9], 0x30
	s_nop 0
	s_load_dwordx2 s[8:9], s[8:9], 0x88
	s_lshl_b32 s26, s80, 7
	s_lshl_b64 s[14:15], s[26:27], 2
	v_ldexp_f32 v0, v2, v0
	v_cndmask_b32_e32 v0, 0, v0, vcc
	v_cndmask_b32_e64 v0, v250, v0, s[2:3]
	s_lshl_b32 s2, s80, 8
	s_waitcnt lgkmcnt(0)
	s_add_u32 s4, s4, s14
	v_mov_b32_e32 v2, 0x3f4ccccd
	s_addc_u32 s5, s5, s15
	v_fmamk_f32 v67, v0, 0xbf19999a, v2
	global_load_dwordx4 v[2:5], v1, s[4:5] offset:48
	global_load_dwordx4 v[6:9], v1, s[4:5] offset:32
	global_load_dwordx4 v[10:13], v1, s[4:5] offset:16
	global_load_dwordx4 v[14:17], v1, s[4:5]
	global_load_dwordx4 v[18:21], v1, s[4:5] offset:176
	global_load_dwordx4 v[22:25], v1, s[4:5] offset:160
	global_load_dwordx4 v[26:29], v1, s[4:5] offset:144
	global_load_dwordx4 v[30:33], v1, s[4:5] offset:128
	global_load_dwordx4 v[34:37], v1, s[4:5] offset:304
	global_load_dwordx4 v[38:41], v1, s[4:5] offset:288
	global_load_dwordx4 v[42:45], v1, s[4:5] offset:272
	global_load_dwordx4 v[46:49], v1, s[4:5] offset:256
	global_load_dwordx4 v[50:53], v1, s[4:5] offset:432
	global_load_dwordx4 v[54:57], v1, s[4:5] offset:416
	global_load_dwordx4 v[58:61], v1, s[4:5] offset:400
	global_load_dwordx4 v[62:65], v1, s[4:5] offset:384
	v_and_b32_e32 v0, 63, v66
	s_mov_b32 s3, s27
	s_lshl_b64 s[2:3], s[2:3], 2
	s_add_u32 s2, s6, s2
	s_addc_u32 s3, s7, s3
	v_mov_b32_e32 v189, v1
	v_mul_u32_u24_e32 v192, 0x1a00, v0
	v_and_b32_e32 v246, 31, v66
	s_ashr_i32 s12, s12, 1
	v_sub_f32_e32 v179, 1.0, v67
	s_andn2_b32 s12, s12, 31
	v_mul_u32_u24_e32 v253, 0x90, v246
	v_mov_b32_e32 v193, v1
	s_lshl_b32 s14, s11, 1
	s_waitcnt vmcnt(8)
	v_fma_f32 v69, v14, v30, 0
	s_waitcnt vmcnt(0)
	v_fma_f32 v68, v46, v62, 0
	v_fmac_f32_e32 v69, v15, v31
	v_fmac_f32_e32 v68, v47, v63
	v_fmac_f32_e32 v69, v16, v32
	v_fmac_f32_e32 v68, v48, v64
	v_fmac_f32_e32 v69, v17, v33
	v_fmac_f32_e32 v68, v49, v65
	v_fmac_f32_e32 v69, v10, v26
	v_fmac_f32_e32 v68, v42, v58
	v_fmac_f32_e32 v69, v11, v27
	v_fmac_f32_e32 v68, v43, v59
	v_fmac_f32_e32 v69, v12, v28
	v_fmac_f32_e32 v68, v44, v60
	v_fmac_f32_e32 v69, v13, v29
	v_fmac_f32_e32 v68, v45, v61
	v_fmac_f32_e32 v69, v6, v22
	v_fmac_f32_e32 v68, v38, v54
	v_fmac_f32_e32 v69, v7, v23
	v_fmac_f32_e32 v68, v39, v55
	v_fmac_f32_e32 v69, v8, v24
	v_fmac_f32_e32 v68, v40, v56
	v_fmac_f32_e32 v69, v9, v25
	v_fmac_f32_e32 v68, v41, v57
	v_fmac_f32_e32 v69, v2, v18
	v_fmac_f32_e32 v68, v34, v50
	v_fmac_f32_e32 v69, v3, v19
	v_fmac_f32_e32 v68, v35, v51
	v_fmac_f32_e32 v69, v4, v20
	v_fmac_f32_e32 v68, v36, v52
	v_fmac_f32_e32 v69, v5, v21
	v_fmac_f32_e32 v68, v37, v53
	global_load_dwordx4 v[2:5], v1, s[4:5] offset:112
	global_load_dwordx4 v[6:9], v1, s[4:5] offset:96
	global_load_dwordx4 v[10:13], v1, s[4:5] offset:80
	global_load_dwordx4 v[38:41], v1, s[4:5] offset:64
	global_load_dwordx4 v[14:17], v1, s[4:5] offset:240
	global_load_dwordx4 v[22:25], v1, s[4:5] offset:224
	global_load_dwordx4 v[34:37], v1, s[4:5] offset:208
	global_load_dwordx4 v[50:53], v1, s[4:5] offset:192
	global_load_dwordx4 v[18:21], v1, s[4:5] offset:368
	global_load_dwordx4 v[30:33], v1, s[4:5] offset:352
	global_load_dwordx4 v[42:45], v1, s[4:5] offset:336
	global_load_dwordx4 v[58:61], v1, s[4:5] offset:320
	global_load_dwordx4 v[26:29], v1, s[4:5] offset:496
	global_load_dwordx4 v[46:49], v1, s[4:5] offset:480
	global_load_dwordx4 v[54:57], v1, s[4:5] offset:464
	global_load_dwordx4 v[62:65], v1, s[4:5] offset:448
	s_mov_b32 s4, 0xc2ce8ed0
	s_mov_b32 s5, 0x42b17218
	s_waitcnt vmcnt(8)
; __device__ __forceinline__ void phase_da(const Params& p, int layer, LAS unsigned char* lds, const bf16_t* Z, bf16_t* Mixed, int tid, int wid, int lane) {
;     ...
;     const float lam_init = 0.8f - 0.6f * expf(-0.3f * (float)layer);
;     float lam;
;     { const float* lf = p.da_lambda + layer * 128; float s1 = 0.f, s2 = 0.f;
;       for (int i = 0; i < 32; ++i) { s1 += lf[i] * lf[32 + i]; s2 += lf[64 + i] * lf[96 + i]; }
;       lam = expf(s1) - expf(s2) + lam_init; }
;     const float c = 0.17677669529663687f * LOG2E;
;     const float* gain = p.da_norm + layer * 256;
;     TL_DECL
	v_fmac_f32_e32 v69, v38, v50
	v_fmac_f32_e32 v69, v39, v51
	v_fmac_f32_e32 v69, v40, v52
	v_fmac_f32_e32 v69, v41, v53
	v_fmac_f32_e32 v69, v10, v34
	v_fmac_f32_e32 v69, v11, v35
	v_fmac_f32_e32 v69, v12, v36
	v_fmac_f32_e32 v69, v13, v37
	s_waitcnt vmcnt(0)
	v_fmac_f32_e32 v68, v58, v62
	v_fmac_f32_e32 v69, v6, v22
	v_fmac_f32_e32 v68, v59, v63
	v_fmac_f32_e32 v69, v7, v23
	v_fmac_f32_e32 v68, v60, v64
	v_fmac_f32_e32 v69, v8, v24
	v_fmac_f32_e32 v68, v61, v65
	v_fmac_f32_e32 v69, v9, v25
	v_fmac_f32_e32 v68, v42, v54
	v_fmac_f32_e32 v69, v2, v14
	v_fmac_f32_e32 v68, v43, v55
	v_fmac_f32_e32 v69, v3, v15
	v_fmac_f32_e32 v68, v44, v56
	v_fmac_f32_e32 v69, v4, v16
	v_fmac_f32_e32 v68, v45, v57
	v_fmac_f32_e32 v69, v5, v17
	v_fmac_f32_e32 v68, v30, v46
	v_mul_f32_e32 v2, 0x3fb8aa3b, v69
	v_fmac_f32_e32 v68, v31, v47
	v_fma_f32 v3, v69, s13, -v2
	v_rndne_f32_e32 v4, v2
	v_fmac_f32_e32 v68, v32, v48
	v_fmac_f32_e32 v3, 0x32a5705f, v69
	v_sub_f32_e32 v2, v2, v4
	v_fmac_f32_e32 v68, v33, v49
	v_add_f32_e32 v2, v2, v3
	v_fmac_f32_e32 v68, v18, v26
	v_exp_f32_e32 v2, v2
	v_cvt_i32_f32_e32 v3, v4
	v_fmac_f32_e32 v68, v19, v27
	v_fmac_f32_e32 v68, v20, v28
	v_fmac_f32_e32 v68, v21, v29
	v_ldexp_f32 v2, v2, v3
	v_mul_f32_e32 v3, 0x3fb8aa3b, v68
	v_fma_f32 v4, v68, s13, -v3
	v_rndne_f32_e32 v5, v3
	v_fmac_f32_e32 v4, 0x32a5705f, v68
	v_sub_f32_e32 v3, v3, v5
	v_add_f32_e32 v3, v3, v4
	v_exp_f32_e32 v3, v3
	v_cvt_i32_f32_e32 v4, v5
	v_cmp_ngt_f32_e32 vcc, s4, v69
	v_bfe_u32 v5, v66, 5, 1
	v_lshlrev_b32_e32 v248, 3, v5
	v_cndmask_b32_e32 v2, 0, v2, vcc
	v_cmp_nlt_f32_e32 vcc, s5, v69
	v_ldexp_f32 v3, v3, v4
	v_lshlrev_b32_e32 v186, 2, v5
	v_cndmask_b32_e32 v2, v250, v2, vcc
	v_cmp_ngt_f32_e32 vcc, s4, v68
	v_lshlrev_b32_e32 v188, 4, v5
	v_xor_b32_e32 v5, 32, v244
	v_cndmask_b32_e32 v3, 0, v3, vcc
	v_cmp_nlt_f32_e32 vcc, s5, v68
	v_lshl_add_u64 v[194:195], s[2:3], 0, v[188:189]
	v_mul_u32_u24_e32 v4, 0xd00, v0
	v_cndmask_b32_e32 v3, v250, v3, vcc
	v_sub_f32_e32 v2, v2, v3
	v_ashrrev_i32_e32 v3, 3, v66
	v_mad_i64_i32 v[172:173], s[4:5], v3, s59, 0
	v_add_f32_e32 v247, v67, v2
	v_lshlrev_b32_e32 v2, 3, v66
	s_movk_i32 s4, 0x48
	v_and_b32_e32 v2, 56, v2
	v_mul_lo_u32 v8, v3, s4
	v_and_b32_e32 v6, -8, v3
	v_lshlrev_b32_e32 v249, 1, v8
	v_lshlrev_b32_e32 v8, 1, v2
	v_add3_u32 v250, 0, v249, v8
	v_mul_lo_u32 v8, v6, s4
	v_and_b32_e32 v18, 0x33, v0
	v_and_b32_e32 v19, 4, v0
	v_lshl_or_b32 v18, v19, 1, v18
	v_and_b32_e32 v19, 8, v0
	v_lshrrev_b32_e32 v19, 1, v19
	v_or_b32_e32 v18, v18, v19
	v_mov_b32_e32 v19, 0
	v_or_b32_e32 v251, v8, v18
	v_or_b32_e32 v8, 7, v3
	v_mad_u64_u32 v[174:175], s[4:5], v8, s4, v[18:19]
	v_add_u32_e32 v8, 64, v3
	v_mad_i64_i32 v[176:177], s[4:5], v8, s59, 0
	v_and_b32_e32 v8, 64, v244
	v_ashrrev_i32_e32 v7, 31, v6
	v_add_u32_e32 v8, 64, v8
	v_cmp_lt_i32_e32 vcc, v5, v8
	v_lshlrev_b64 v[198:199], 1, v[6:7]
	v_mad_u64_u32 v[6:7], s[2:3], v0, s59, v[198:199]
	v_cndmask_b32_e32 v5, v244, v5, vcc
	v_lshlrev_b32_e32 v239, 2, v5
	v_or_b32_e32 v5, 32, v0
	v_lshl_add_u64 v[6:7], s[8:9], 0, v[6:7]
	s_mov_b64 s[2:3], 0x138c00
	v_and_b32_e32 v0, 7, v66
	v_lshl_add_u64 v[200:201], v[6:7], 0, s[2:3]
	v_lshl_or_b32 v6, v0, 4, v172
	v_mov_b32_e32 v7, v173
	v_mul_u32_u24_e32 v240, 0x90, v5
	s_movk_i32 s4, 0x90
	v_add_u32_e32 v3, 0x80, v3
	v_lshl_add_u64 v[6:7], s[8:9], 0, v[6:7]
	s_mov_b64 s[2:3], 0x138a00
	v_lshl_add_u32 v252, v251, 1, 0
	v_lshl_add_u32 v175, v174, 1, 0
	v_mad_u32_u24 v242, v246, s4, 0
	v_add3_u32 v243, 0, v240, v188
	v_or_b32_e32 v245, 32, v186
	v_mad_i64_i32 v[190:191], s[4:5], v3, s59, 0
	v_lshl_add_u64 v[196:197], s[8:9], 0, v[188:189]
	s_lshl_b32 s13, s10, 1
	v_lshl_add_u64 v[202:203], v[6:7], 0, s[2:3]
	v_lshlrev_b32_e32 v204, 1, v2
	v_lshlrev_b32_e32 v206, 1, v4
	v_lshlrev_b32_e32 v0, 1, v186
	s_branch .LBB0_232

; __device__ __forceinline__ void attn_sub_x2(float& m1, float& l1, f32x16& oa0, f32x16& oa1, float& m2, float& l2, f32x16& ob0, f32x16& ob1, ...
;     ...
;     float p1[16], p2[16]; f32x2_t a1 = {0.f, 0.f}, a2 = {0.f, 0.f}; const f32x2_t c2 = {c, c}, mA = {mn1, mn1}, mB = {mn2, mn2};
; #pragma unroll
;     for (int i = 0; i < 8; ++i) { f32x2_t t1 = {s1[2 * i], s1[2 * i + 1]}, t2 = {s2[2 * i], s2[2 * i + 1]}; t1 = (t1 - mA) * c2; t2 = (t2 - mB) * c2;
;         p1[2 * i] = ex2(t1.x); p1[2 * i + 1] = ex2(t1.y); p2[2 * i] = ex2(t2.x); p2[2 * i + 1] = ex2(t2.y);
;         const f32x2_t u1 = {p1[2 * i], p1[2 * i + 1]}, u2 = {p2[2 * i], p2[2 * i + 1]}; a1 += u1; a2 += u2; }
;     l1 = l1 * al1 + (a1.x + a1.y); l2 = l2 * al2 + (a2.x + a2.y);
; #pragma unroll
;     for (int s2i = 0; s2i < 2; ++s2i) {
;         const bf16x8 pb1 = pack8(p1[8 * s2i + 0], p1[8 * s2i + 1], p1[8 * s2i + 2], p1[8 * s2i + 3], p1[8 * s2i + 4], p1[8 * s2i + 5], p1[8 * s2i + 6], p1[8 * s2i + 7]);
;         const bf16x8 pb2 = pack8(p2[8 * s2i + 0], p2[8 * s2i + 1], p2[8 * s2i + 2], p2[8 * s2i + 3], p2[8 * s2i + 4], p2[8 * s2i + 5], p2[8 * s2i + 6], p2[8 * s2i + 7]);
;         const LAS bf16_t* vp = Vt + r * VP + kr0 + 16 * s2i + 4 * h;
;         const u32x2 a0l = *(const LAS u32x2*)vp, a0h = *(const LAS u32x2*)(vp + 8);
;         const u32x2 a1l = *(const LAS u32x2*)(vp + 32 * VP), a1h = *(const LAS u32x2*)(vp + 32 * VP + 8);
;         const u32x4 v0 = {a0l.x, a0l.y, a0h.x, a0h.y}, v1 = {a1l.x, a1l.y, a1h.x, a1h.y};
;         oa0 = __builtin_amdgcn_mfma_f32_32x32x16_bf16(__builtin_bit_cast(bf16x8, v0), pb1, oa0, 0, 0, 0);
;         ob0 = __builtin_amdgcn_mfma_f32_32x32x16_bf16(__builtin_bit_cast(bf16x8, v0), pb2, ob0, 0, 0, 0);
;         oa1 = __builtin_amdgcn_mfma_f32_32x32x16_bf16(__builtin_bit_cast(bf16x8, v1), pb1, oa1, 0, 0, 0);
;         ob1 = __builtin_amdgcn_mfma_f32_32x32x16_bf16(__builtin_bit_cast(bf16x8, v1), pb2, ob1, 0, 0, 0);
;     }
; }
; __device__ __forceinline__ void phase_da(const Params& p, int layer, LAS unsigned char* lds, const bf16_t* Z, bf16_t* Mixed, int tid, int wid, int lane) {
;     ...
;                     if (t == 0 && sub == 0) {
;                         attn_sub_x2(m1, l1, oa0, oa1, m2, l2, ob0, ob1, qf1, qf2, Ks, Vt, 0, k0, qpos, 1.0f, nm, r, h);
;                         l1 += __shfl_xor(l1, 32); l2 += __shfl_xor(l2, 32);
; #pragma unroll
.LBB0_241:
	v_pk_add_f32 v[2:3], v[2:3], v[232:233] op_sel_hi:[1,0] neg_lo:[0,1] neg_hi:[0,1]
	v_pk_add_f32 v[18:19], v[18:19], v[98:99] op_sel_hi:[1,0] neg_lo:[0,1] neg_hi:[0,1]
	v_exp_f32_e32 v2, v2
	v_exp_f32_e32 v3, v3
	v_exp_f32_e32 v18, v18
	v_exp_f32_e32 v19, v19
	v_pk_add_f32 v[4:5], v[4:5], v[232:233] op_sel_hi:[1,0] neg_lo:[0,1] neg_hi:[0,1]
	v_pk_add_f32 v[20:21], v[20:21], v[98:99] op_sel_hi:[1,0] neg_lo:[0,1] neg_hi:[0,1]
	v_exp_f32_e32 v4, v4
	v_exp_f32_e32 v5, v5
	v_exp_f32_e32 v82, v20
	v_exp_f32_e32 v83, v21
	v_pk_add_f32 v[6:7], v[6:7], v[232:233] op_sel_hi:[1,0] neg_lo:[0,1] neg_hi:[0,1]
	v_pk_add_f32 v[22:23], v[22:23], v[98:99] op_sel_hi:[1,0] neg_lo:[0,1] neg_hi:[0,1]
	v_exp_f32_e32 v6, v6
	v_exp_f32_e32 v7, v7
	v_exp_f32_e32 v22, v22
	v_exp_f32_e32 v23, v23
	v_pk_add_f32 v[8:9], v[8:9], v[232:233] op_sel_hi:[1,0] neg_lo:[0,1] neg_hi:[0,1]
	v_pk_add_f32 v[24:25], v[24:25], v[98:99] op_sel_hi:[1,0] neg_lo:[0,1] neg_hi:[0,1]
	v_exp_f32_e32 v8, v8
	v_exp_f32_e32 v9, v9
	v_exp_f32_e32 v84, v24
	v_exp_f32_e32 v85, v25
	v_pk_add_f32 v[10:11], v[10:11], v[232:233] op_sel_hi:[1,0] neg_lo:[0,1] neg_hi:[0,1]
	v_pk_add_f32 v[26:27], v[26:27], v[98:99] op_sel_hi:[1,0] neg_lo:[0,1] neg_hi:[0,1]
	v_pk_add_f32 v[20:21], v[2:3], 0 op_sel_hi:[1,0]
	v_pk_add_f32 v[68:69], v[18:19], 0 op_sel_hi:[1,0]
	v_exp_f32_e32 v10, v10
	v_exp_f32_e32 v11, v11
	v_exp_f32_e32 v86, v26
	v_exp_f32_e32 v87, v27
	v_pk_add_f32 v[20:21], v[4:5], v[20:21]
	v_pk_add_f32 v[68:69], v[82:83], v[68:69]
	v_pk_add_f32 v[20:21], v[6:7], v[20:21]
	v_pk_add_f32 v[24:25], v[22:23], v[68:69]
	v_pk_add_f32 v[20:21], v[8:9], v[20:21]
	v_pk_add_f32 v[24:25], v[84:85], v[24:25]
	v_pk_add_f32 v[12:13], v[12:13], v[232:233] op_sel_hi:[1,0] neg_lo:[0,1] neg_hi:[0,1]
	v_pk_add_f32 v[26:27], v[28:29], v[98:99] op_sel_hi:[1,0] neg_lo:[0,1] neg_hi:[0,1]
	v_exp_f32_e32 v28, v12
	v_exp_f32_e32 v29, v13
	v_exp_f32_e32 v88, v26
	v_exp_f32_e32 v89, v27
	v_pk_add_f32 v[12:13], v[10:11], v[20:21]
	v_pk_add_f32 v[20:21], v[86:87], v[24:25]
	v_pk_add_f32 v[14:15], v[14:15], v[232:233] op_sel_hi:[1,0] neg_lo:[0,1] neg_hi:[0,1]
	v_pk_add_f32 v[24:25], v[30:31], v[98:99] op_sel_hi:[1,0] neg_lo:[0,1] neg_hi:[0,1]
	v_exp_f32_e32 v26, v14
	v_exp_f32_e32 v27, v15
	v_exp_f32_e32 v90, v24
	v_exp_f32_e32 v91, v25
	v_pk_add_f32 v[14:15], v[16:17], v[232:233] op_sel_hi:[1,0] neg_lo:[0,1] neg_hi:[0,1]
	v_pk_add_f32 v[16:17], v[32:33], v[98:99] op_sel_hi:[1,0] neg_lo:[0,1] neg_hi:[0,1]
	v_pk_add_f32 v[20:21], v[88:89], v[20:21]
	v_exp_f32_e32 v16, v16
	v_exp_f32_e32 v17, v17
	v_exp_f32_e32 v30, v14
	v_exp_f32_e32 v31, v15
	v_pk_add_f32 v[14:15], v[90:91], v[20:21]
	v_pk_add_f32 v[12:13], v[28:29], v[12:13]
	v_pk_add_f32 v[20:21], v[16:17], v[14:15]
	v_pk_add_f32 v[12:13], v[26:27], v[12:13]
	v_lshl_add_u32 v25, v248, 1, v242
	v_add_f32_e32 v20, v20, v21
	v_pk_add_f32 v[12:13], v[30:31], v[12:13]
	v_add_u32_e32 v32, 0x3000, v25
	v_add_f32_e32 v92, v20, v66
	v_cvt_pk_bf16_f32 v20, v18, v19
	v_add_u32_e32 v18, 0x2000, v25
	v_add_f32_e32 v24, v12, v13
	ds_read_b128 v[12:15], v32 offset:1536
	v_cvt_pk_bf16_f32 v2, v2, v3
	v_cvt_pk_bf16_f32 v3, v4, v5
	v_cvt_pk_bf16_f32 v4, v6, v7
	v_cvt_pk_bf16_f32 v5, v8, v9
	ds_read_b128 v[6:9], v18 offset:1024
	v_add_f32_e32 v33, v24, v67
	v_cvt_pk_bf16_f32 v24, v10, v11
	ds_bpermute_b32 v11, v239, v92
	v_mov_b32_e32 v35, v34
	v_mov_b32_e32 v36, v34
	v_mov_b32_e32 v37, v34
	v_mov_b32_e32 v38, v34
	v_mov_b32_e32 v39, v34
	v_mov_b32_e32 v40, v34
	v_mov_b32_e32 v41, v34
	v_mov_b32_e32 v42, v34
	v_mov_b32_e32 v43, v34
	v_mov_b32_e32 v44, v34
	v_mov_b32_e32 v45, v34
	v_mov_b32_e32 v46, v34
	v_mov_b32_e32 v47, v34
	v_mov_b32_e32 v48, v34
	v_mov_b32_e32 v49, v34
	v_mov_b32_e32 v51, v50
	v_mov_b32_e32 v52, v50
	v_mov_b32_e32 v53, v50
	v_mov_b32_e32 v54, v50
	v_mov_b32_e32 v55, v50
	v_mov_b32_e32 v56, v50
	v_mov_b32_e32 v57, v50
	v_mov_b32_e32 v58, v50
	v_mov_b32_e32 v59, v50
	v_mov_b32_e32 v60, v50
	v_mov_b32_e32 v61, v50
	v_mov_b32_e32 v62, v50
	v_mov_b32_e32 v63, v50
	v_mov_b32_e32 v64, v50
	v_mov_b32_e32 v65, v50
	ds_read_b128 v[100:103], v32 offset:1568
	v_cvt_pk_bf16_f32 v25, v28, v29
	v_cvt_pk_bf16_f32 v26, v26, v27
	v_cvt_pk_bf16_f32 v27, v30, v31
	v_cvt_pk_bf16_f32 v21, v82, v83
	v_cvt_pk_bf16_f32 v22, v22, v23
	v_cvt_pk_bf16_f32 v23, v84, v85
	ds_read_b128 v[28:31], v18 offset:1056
	s_waitcnt lgkmcnt(4)
	v_mfma_f32_32x32x16_bf16 v[66:81], v[12:15], v[2:5], v[34:49]
	v_cvt_pk_bf16_f32 v104, v86, v87
	v_cvt_pk_bf16_f32 v105, v88, v89
	v_cvt_pk_bf16_f32 v106, v90, v91
	s_waitcnt lgkmcnt(2)
	v_add_f32_e32 v18, v92, v11
	v_cvt_pk_bf16_f32 v107, v16, v17
	ds_bpermute_b32 v10, v239, v33
	v_mov_b32_e32 v19, v18
	v_mfma_f32_32x32x16_bf16 v[34:49], v[6:9], v[2:5], v[34:49]
	v_mov_b32_e32 v32, v18
	v_mov_b32_e32 v233, v98
	s_waitcnt lgkmcnt(0)
	v_add_f32_e32 v2, v33, v10
	v_mov_b32_e32 v3, v2
	v_mov_b32_e32 v4, v2
	v_mov_b32_e32 v5, v2
	v_mov_b32_e32 v10, v2
	v_mfma_f32_32x32x16_bf16 v[82:97], v[6:9], v[20:23], v[50:65]
	v_mov_b32_e32 v6, v2
	v_mov_b32_e32 v7, v2
	v_mov_b32_e32 v8, v2
	v_mov_b32_e32 v9, v2
	v_mov_b32_e32 v11, v2
	v_mov_b32_e32 v16, v2
	v_mov_b32_e32 v17, v2
	v_mfma_f32_32x32x16_bf16 v[50:65], v[12:15], v[20:23], v[50:65]
	v_mov_b32_e32 v12, v2
	v_mov_b32_e32 v13, v2
	v_mov_b32_e32 v14, v2
	v_mov_b32_e32 v15, v2
	v_mov_b32_e32 v20, v18
	v_mov_b32_e32 v21, v18
	v_mov_b32_e32 v22, v18
	v_mfma_f32_32x32x16_bf16 v[66:81], v[100:103], v[24:27], v[66:81]
	v_mov_b32_e32 v23, v18
	v_mov_b32_e32 v33, v18
	v_mfma_f32_32x32x16_bf16 v[34:49], v[28:31], v[24:27], v[34:49]
	v_mov_b32_e32 v24, v18
	v_mov_b32_e32 v25, v18
	v_mov_b32_e32 v26, v18
	v_mov_b32_e32 v27, v18
	v_mfma_f32_32x32x16_bf16 v[82:97], v[28:31], v[104:107], v[82:97]
	v_mov_b32_e32 v28, v18
	v_mov_b32_e32 v29, v18
	v_mov_b32_e32 v30, v18
	v_mov_b32_e32 v31, v18
	v_mfma_f32_32x32x16_bf16 v[50:65], v[100:103], v[104:107], v[50:65]
	s_xor_b64 s[2:3], s[6:7], -1
	s_or_b32 s7, s17, 31
	s_cmp_lt_i32 s7, 32
	s_cbranch_scc1 .LBB0_245

; #define LAS __attribute__((address_space(3)))
; __device__ __forceinline__ float ex2(float x) { return __builtin_amdgcn_exp2f(x); }
; __device__ __forceinline__ void attn_fast_x2(float mr1, f32x16& L1, f32x16& oa0, f32x16& oa1, float mr2, f32x16& L2, f32x16& ob0, f32x16& ob1, ...
;     ...
;     float p1[16], p2[16];
; #pragma unroll
;     for (int i = 0; i < 16; ++i) { p1[i] = ex2(s1[i]); p2[i] = ex2(s2[i]); }
;     const u32x4 onesu = {0x3f803f80u, 0x3f803f80u, 0x3f803f80u, 0x3f803f80u}; const bf16x8 ones = __builtin_bit_cast(bf16x8, onesu);
; #pragma unroll
;     for (int s2i = 0; s2i < 2; ++s2i) {
;         const bf16x8 pb1 = pack8(p1[8 * s2i + 0], p1[8 * s2i + 1], p1[8 * s2i + 2], p1[8 * s2i + 3], p1[8 * s2i + 4], p1[8 * s2i + 5], p1[8 * s2i + 6], p1[8 * s2i + 7]);
;         const bf16x8 pb2 = pack8(p2[8 * s2i + 0], p2[8 * s2i + 1], p2[8 * s2i + 2], p2[8 * s2i + 3], p2[8 * s2i + 4], p2[8 * s2i + 5], p2[8 * s2i + 6], p2[8 * s2i + 7]);
;         const LAS bf16_t* vp = Vt + r * VP + kr0 + 16 * s2i + 4 * h;
;         const u32x2 a0l = *(const LAS u32x2*)vp, a0h = *(const LAS u32x2*)(vp + 8);
;         const u32x2 a1l = *(const LAS u32x2*)(vp + 32 * VP), a1h = *(const LAS u32x2*)(vp + 32 * VP + 8);
;         const u32x4 v0 = {a0l.x, a0l.y, a0h.x, a0h.y}, v1 = {a1l.x, a1l.y, a1h.x, a1h.y};
;         oa0 = __builtin_amdgcn_mfma_f32_32x32x16_bf16(__builtin_bit_cast(bf16x8, v0), pb1, oa0, 0, 0, 0);
;         ob0 = __builtin_amdgcn_mfma_f32_32x32x16_bf16(__builtin_bit_cast(bf16x8, v0), pb2, ob0, 0, 0, 0);
;         oa1 = __builtin_amdgcn_mfma_f32_32x32x16_bf16(__builtin_bit_cast(bf16x8, v1), pb1, oa1, 0, 0, 0);
;         ob1 = __builtin_amdgcn_mfma_f32_32x32x16_bf16(__builtin_bit_cast(bf16x8, v1), pb2, ob1, 0, 0, 0);
;         L1 = __builtin_amdgcn_mfma_f32_32x32x16_bf16(ones, pb1, L1, 0, 0, 0);
;         L2 = __builtin_amdgcn_mfma_f32_32x32x16_bf16(ones, pb2, L2, 0, 0, 0);
;     }
.LBB0_244:
	s_nop 7
	v_exp_f32_e32 v114, v114
	v_exp_f32_e32 v115, v115
	v_exp_f32_e32 v118, v118
	v_exp_f32_e32 v119, v119
	v_exp_f32_e32 v116, v116
	v_exp_f32_e32 v117, v117
	v_exp_f32_e32 v138, v102
	v_cvt_pk_bf16_f32 v102, v114, v115
	v_lshl_add_u32 v114, v248, 1, v242
	v_exp_f32_e32 v98, v98
	v_exp_f32_e32 v99, v99
	v_exp_f32_e32 v100, v100
	v_exp_f32_e32 v101, v101
	v_exp_f32_e32 v139, v103
	v_exp_f32_e32 v120, v120
	v_exp_f32_e32 v140, v104
	v_exp_f32_e32 v121, v121
	v_exp_f32_e32 v141, v105
	v_exp_f32_e32 v146, v110
	v_cvt_pk_bf16_f32 v104, v118, v119
	v_add_u32_e32 v110, 0x2000, v114
	v_add_u32_e32 v118, 0x3000, v114
	v_exp_f32_e32 v142, v106
	v_exp_f32_e32 v143, v107
	v_exp_f32_e32 v144, v108
	v_exp_f32_e32 v145, v109
	v_exp_f32_e32 v147, v111
	v_exp_f32_e32 v164, v112
	v_exp_f32_e32 v165, v113
	v_cvt_pk_bf16_f32 v103, v116, v117
	ds_read_b128 v[106:109], v110 offset:1088
	ds_read_b128 v[110:113], v110 offset:1120
	ds_read_b128 v[114:117], v118 offset:1600
	v_cvt_pk_bf16_f32 v105, v120, v121
	v_cvt_pk_bf16_f32 v98, v98, v99
	v_cvt_pk_bf16_f32 v99, v100, v101
	v_cvt_pk_bf16_f32 v100, v138, v139
	v_cvt_pk_bf16_f32 v101, v140, v141
	s_mov_b32 s30, s28
	s_mov_b32 s31, s28
	s_waitcnt lgkmcnt(2)
	v_mfma_f32_32x32x16_bf16 v[34:49], v[106:109], v[102:105], v[34:49]
	s_mov_b32 s29, s28
	v_exp_f32_e32 v122, v122
	v_exp_f32_e32 v123, v123
	v_exp_f32_e32 v124, v124
	v_exp_f32_e32 v125, v125
	v_exp_f32_e32 v126, v126
	v_exp_f32_e32 v127, v127
	v_mfma_f32_32x32x16_bf16 v[82:97], v[106:109], v[98:101], v[82:97]
	v_mov_b64_e32 v[108:109], s[30:31]
	v_mov_b64_e32 v[106:107], s[28:29]
	v_exp_f32_e32 v128, v128
	v_exp_f32_e32 v129, v129
	s_waitcnt lgkmcnt(0)
	v_mfma_f32_32x32x16_bf16 v[66:81], v[114:117], v[102:105], v[66:81]
	v_mfma_f32_32x32x16_bf16 v[50:65], v[114:117], v[98:101], v[50:65]
	ds_read_b128 v[114:117], v118 offset:1632
	v_mfma_f32_32x32x16_bf16 v[2:17], v[106:109], v[102:105], v[2:17]
	v_cvt_pk_bf16_f32 v102, v142, v143
	v_cvt_pk_bf16_f32 v103, v144, v145
	v_cvt_pk_bf16_f32 v104, v146, v147
	v_cvt_pk_bf16_f32 v105, v164, v165
	v_mfma_f32_32x32x16_bf16 v[18:33], v[106:109], v[98:101], v[18:33]
	v_cvt_pk_bf16_f32 v98, v122, v123
	v_cvt_pk_bf16_f32 v99, v124, v125
	v_cvt_pk_bf16_f32 v100, v126, v127
	v_cvt_pk_bf16_f32 v101, v128, v129
	s_nop 1
	v_mfma_f32_32x32x16_bf16 v[34:49], v[110:113], v[98:101], v[34:49]
	v_mfma_f32_32x32x16_bf16 v[82:97], v[110:113], v[102:105], v[82:97]
	s_waitcnt lgkmcnt(0)
	v_mfma_f32_32x32x16_bf16 v[66:81], v[114:117], v[98:101], v[66:81]
	v_mfma_f32_32x32x16_bf16 v[50:65], v[114:117], v[102:105], v[50:65]
	v_mfma_f32_32x32x16_bf16 v[2:17], v[106:109], v[98:101], v[2:17]
	v_mfma_f32_32x32x16_bf16 v[18:33], v[106:109], v[102:105], v[18:33]

; #define LAS __attribute__((address_space(3)))
; __device__ __forceinline__ float ex2(float x) { return __builtin_amdgcn_exp2f(x); }
; __device__ __forceinline__ void attn_fast_x2(float mr1, f32x16& L1, f32x16& oa0, f32x16& oa1, float mr2, f32x16& L2, f32x16& ob0, f32x16& ob1, ...
;     ...
;     float p1[16], p2[16];
; #pragma unroll
;     for (int i = 0; i < 16; ++i) { p1[i] = ex2(s1[i]); p2[i] = ex2(s2[i]); }
;     const u32x4 onesu = {0x3f803f80u, 0x3f803f80u, 0x3f803f80u, 0x3f803f80u}; const bf16x8 ones = __builtin_bit_cast(bf16x8, onesu);
; #pragma unroll
;     for (int s2i = 0; s2i < 2; ++s2i) {
;         const bf16x8 pb1 = pack8(p1[8 * s2i + 0], p1[8 * s2i + 1], p1[8 * s2i + 2], p1[8 * s2i + 3], p1[8 * s2i + 4], p1[8 * s2i + 5], p1[8 * s2i + 6], p1[8 * s2i + 7]);
;         const bf16x8 pb2 = pack8(p2[8 * s2i + 0], p2[8 * s2i + 1], p2[8 * s2i + 2], p2[8 * s2i + 3], p2[8 * s2i + 4], p2[8 * s2i + 5], p2[8 * s2i + 6], p2[8 * s2i + 7]);
;         const LAS bf16_t* vp = Vt + r * VP + kr0 + 16 * s2i + 4 * h;
;         const u32x2 a0l = *(const LAS u32x2*)vp, a0h = *(const LAS u32x2*)(vp + 8);
;         const u32x2 a1l = *(const LAS u32x2*)(vp + 32 * VP), a1h = *(const LAS u32x2*)(vp + 32 * VP + 8);
;         const u32x4 v0 = {a0l.x, a0l.y, a0h.x, a0h.y}, v1 = {a1l.x, a1l.y, a1h.x, a1h.y};
;         oa0 = __builtin_amdgcn_mfma_f32_32x32x16_bf16(__builtin_bit_cast(bf16x8, v0), pb1, oa0, 0, 0, 0);
;         ob0 = __builtin_amdgcn_mfma_f32_32x32x16_bf16(__builtin_bit_cast(bf16x8, v0), pb2, ob0, 0, 0, 0);
;         oa1 = __builtin_amdgcn_mfma_f32_32x32x16_bf16(__builtin_bit_cast(bf16x8, v1), pb1, oa1, 0, 0, 0);
;         ob1 = __builtin_amdgcn_mfma_f32_32x32x16_bf16(__builtin_bit_cast(bf16x8, v1), pb2, ob1, 0, 0, 0);
;         L1 = __builtin_amdgcn_mfma_f32_32x32x16_bf16(ones, pb1, L1, 0, 0, 0);
;         L2 = __builtin_amdgcn_mfma_f32_32x32x16_bf16(ones, pb2, L2, 0, 0, 0);
;     }
.LBB0_251:
	s_nop 6
	v_exp_f32_e32 v99, v116
	v_exp_f32_e32 v101, v117
	v_exp_f32_e32 v106, v120
	v_exp_f32_e32 v107, v121
	v_exp_f32_e32 v112, v122
	v_exp_f32_e32 v115, v123
	v_exp_f32_e32 v100, v132
	v_exp_f32_e32 v102, v133
	v_exp_f32_e32 v103, v118
	v_exp_f32_e32 v108, v134
	v_exp_f32_e32 v105, v119
	v_exp_f32_e32 v109, v135
	v_exp_f32_e32 v110, v136
	v_exp_f32_e32 v111, v137
	v_exp_f32_e32 v113, v138
	v_exp_f32_e32 v116, v139
	v_cvt_pk_bf16_f32 v104, v99, v101
	v_lshl_add_u32 v99, v248, 1, v181
	v_cvt_pk_bf16_f32 v106, v106, v107
	v_cvt_pk_bf16_f32 v107, v112, v115
	v_add_u32_e32 v112, 0x2000, v99
	v_add_u32_e32 v99, 0x3000, v99
	v_cvt_pk_bf16_f32 v105, v103, v105
	v_cvt_pk_bf16_f32 v100, v100, v102
	v_cvt_pk_bf16_f32 v101, v108, v109
	v_cvt_pk_bf16_f32 v102, v110, v111
	v_cvt_pk_bf16_f32 v103, v113, v116
	ds_read_b128 v[108:111], v112 offset:1024
	ds_read_b128 v[116:119], v112 offset:1056
	ds_read_b128 v[120:123], v99 offset:1536
	s_waitcnt lgkmcnt(2)
	v_mfma_f32_32x32x16_bf16 v[34:49], v[108:111], v[104:107], v[34:49]
	v_exp_f32_e32 v124, v124
	v_exp_f32_e32 v132, v140
	v_exp_f32_e32 v125, v125
	v_exp_f32_e32 v133, v141
	v_exp_f32_e32 v126, v126
	v_exp_f32_e32 v134, v142
	v_mfma_f32_32x32x16_bf16 v[82:97], v[108:111], v[100:103], v[82:97]
	v_exp_f32_e32 v127, v127
	v_exp_f32_e32 v135, v143
	v_exp_f32_e32 v128, v128
	v_exp_f32_e32 v136, v144
	v_exp_f32_e32 v129, v129
	s_waitcnt lgkmcnt(0)
	v_mfma_f32_32x32x16_bf16 v[66:81], v[120:123], v[104:107], v[66:81]
	v_exp_f32_e32 v137, v145
	v_exp_f32_e32 v130, v130
	v_exp_f32_e32 v138, v146
	v_exp_f32_e32 v131, v131
	v_exp_f32_e32 v139, v147
	v_mfma_f32_32x32x16_bf16 v[50:65], v[120:123], v[100:103], v[50:65]
	ds_read_b128 v[120:123], v99 offset:1568
	v_mfma_f32_32x32x16_bf16 v[2:17], v[222:225], v[104:107], v[2:17]
	v_cvt_pk_bf16_f32 v104, v132, v133
	v_cvt_pk_bf16_f32 v105, v134, v135
	v_cvt_pk_bf16_f32 v106, v136, v137
	v_cvt_pk_bf16_f32 v107, v138, v139
	v_mfma_f32_32x32x16_bf16 v[18:33], v[222:225], v[100:103], v[18:33]
	v_cvt_pk_bf16_f32 v100, v124, v125
	v_cvt_pk_bf16_f32 v101, v126, v127
	v_cvt_pk_bf16_f32 v102, v128, v129
	v_cvt_pk_bf16_f32 v103, v130, v131
	s_nop 1
	v_mfma_f32_32x32x16_bf16 v[34:49], v[116:119], v[100:103], v[34:49]
	v_mfma_f32_32x32x16_bf16 v[82:97], v[116:119], v[104:107], v[82:97]
	s_waitcnt lgkmcnt(0)
	v_mfma_f32_32x32x16_bf16 v[66:81], v[120:123], v[100:103], v[66:81]
	v_mfma_f32_32x32x16_bf16 v[50:65], v[120:123], v[104:107], v[50:65]
	v_mfma_f32_32x32x16_bf16 v[2:17], v[222:225], v[100:103], v[2:17]
	v_mfma_f32_32x32x16_bf16 v[18:33], v[222:225], v[104:107], v[18:33]

; #define LAS __attribute__((address_space(3)))
; __device__ __forceinline__ float ex2(float x) { return __builtin_amdgcn_exp2f(x); }
; __device__ __forceinline__ void attn_fast_x2(float mr1, f32x16& L1, f32x16& oa0, f32x16& oa1, float mr2, f32x16& L2, f32x16& ob0, f32x16& ob1, ...
;     ...
;     float p1[16], p2[16];
; #pragma unroll
;     for (int i = 0; i < 16; ++i) { p1[i] = ex2(s1[i]); p2[i] = ex2(s2[i]); }
;     const u32x4 onesu = {0x3f803f80u, 0x3f803f80u, 0x3f803f80u, 0x3f803f80u}; const bf16x8 ones = __builtin_bit_cast(bf16x8, onesu);
; #pragma unroll
;     for (int s2i = 0; s2i < 2; ++s2i) {
;         const bf16x8 pb1 = pack8(p1[8 * s2i + 0], p1[8 * s2i + 1], p1[8 * s2i + 2], p1[8 * s2i + 3], p1[8 * s2i + 4], p1[8 * s2i + 5], p1[8 * s2i + 6], p1[8 * s2i + 7]);
;         const bf16x8 pb2 = pack8(p2[8 * s2i + 0], p2[8 * s2i + 1], p2[8 * s2i + 2], p2[8 * s2i + 3], p2[8 * s2i + 4], p2[8 * s2i + 5], p2[8 * s2i + 6], p2[8 * s2i + 7]);
;         const LAS bf16_t* vp = Vt + r * VP + kr0 + 16 * s2i + 4 * h;
;         const u32x2 a0l = *(const LAS u32x2*)vp, a0h = *(const LAS u32x2*)(vp + 8);
;         const u32x2 a1l = *(const LAS u32x2*)(vp + 32 * VP), a1h = *(const LAS u32x2*)(vp + 32 * VP + 8);
;         const u32x4 v0 = {a0l.x, a0l.y, a0h.x, a0h.y}, v1 = {a1l.x, a1l.y, a1h.x, a1h.y};
;         oa0 = __builtin_amdgcn_mfma_f32_32x32x16_bf16(__builtin_bit_cast(bf16x8, v0), pb1, oa0, 0, 0, 0);
;         ob0 = __builtin_amdgcn_mfma_f32_32x32x16_bf16(__builtin_bit_cast(bf16x8, v0), pb2, ob0, 0, 0, 0);
;         oa1 = __builtin_amdgcn_mfma_f32_32x32x16_bf16(__builtin_bit_cast(bf16x8, v1), pb1, oa1, 0, 0, 0);
;         ob1 = __builtin_amdgcn_mfma_f32_32x32x16_bf16(__builtin_bit_cast(bf16x8, v1), pb2, ob1, 0, 0, 0);
;         L1 = __builtin_amdgcn_mfma_f32_32x32x16_bf16(ones, pb1, L1, 0, 0, 0);
;         L2 = __builtin_amdgcn_mfma_f32_32x32x16_bf16(ones, pb2, L2, 0, 0, 0);
;     }
.LBB0_255:
	s_nop 7
	v_exp_f32_e32 v114, v114
	v_exp_f32_e32 v115, v115
	v_exp_f32_e32 v118, v118
	v_exp_f32_e32 v119, v119
	v_exp_f32_e32 v116, v116
	v_exp_f32_e32 v117, v117
	v_exp_f32_e32 v130, v102
	v_cvt_pk_bf16_f32 v102, v114, v115
	v_lshl_add_u32 v114, v248, 1, v181
	v_exp_f32_e32 v98, v98
	v_exp_f32_e32 v99, v99
	v_exp_f32_e32 v100, v100
	v_exp_f32_e32 v101, v101
	v_exp_f32_e32 v131, v103
	v_exp_f32_e32 v120, v120
	v_exp_f32_e32 v132, v104
	v_exp_f32_e32 v121, v121
	v_exp_f32_e32 v133, v105
	v_exp_f32_e32 v138, v110
	v_cvt_pk_bf16_f32 v104, v118, v119
	v_add_u32_e32 v110, 0x2000, v114
	v_add_u32_e32 v118, 0x3000, v114
	v_exp_f32_e32 v134, v106
	v_exp_f32_e32 v135, v107
	v_exp_f32_e32 v136, v108
	v_exp_f32_e32 v137, v109
	v_exp_f32_e32 v139, v111
	v_exp_f32_e32 v140, v112
	v_exp_f32_e32 v141, v113
	v_cvt_pk_bf16_f32 v103, v116, v117
	ds_read_b128 v[106:109], v110 offset:1088
	ds_read_b128 v[110:113], v110 offset:1120
	ds_read_b128 v[114:117], v118 offset:1600
	v_cvt_pk_bf16_f32 v105, v120, v121
	v_cvt_pk_bf16_f32 v98, v98, v99
	v_cvt_pk_bf16_f32 v99, v100, v101
	v_cvt_pk_bf16_f32 v100, v130, v131
	v_cvt_pk_bf16_f32 v101, v132, v133
	s_waitcnt lgkmcnt(2)
	v_mfma_f32_32x32x16_bf16 v[34:49], v[106:109], v[102:105], v[34:49]
	v_exp_f32_e32 v122, v122
	v_exp_f32_e32 v123, v123
	v_exp_f32_e32 v124, v124
	v_exp_f32_e32 v125, v125
	v_exp_f32_e32 v126, v126
	v_exp_f32_e32 v127, v127
	v_mfma_f32_32x32x16_bf16 v[82:97], v[106:109], v[98:101], v[82:97]
	v_exp_f32_e32 v128, v128
	v_exp_f32_e32 v129, v129
	s_waitcnt lgkmcnt(0)
	v_mfma_f32_32x32x16_bf16 v[66:81], v[114:117], v[102:105], v[66:81]
	v_mfma_f32_32x32x16_bf16 v[50:65], v[114:117], v[98:101], v[50:65]
	ds_read_b128 v[114:117], v118 offset:1632
	v_mfma_f32_32x32x16_bf16 v[2:17], v[222:225], v[102:105], v[2:17]
	v_cvt_pk_bf16_f32 v102, v134, v135
	v_cvt_pk_bf16_f32 v103, v136, v137
	v_cvt_pk_bf16_f32 v104, v138, v139
	v_cvt_pk_bf16_f32 v105, v140, v141
	v_mfma_f32_32x32x16_bf16 v[18:33], v[222:225], v[98:101], v[18:33]
	v_cvt_pk_bf16_f32 v98, v122, v123
	v_cvt_pk_bf16_f32 v99, v124, v125
	v_cvt_pk_bf16_f32 v100, v126, v127
	v_cvt_pk_bf16_f32 v101, v128, v129
	s_nop 1
	v_mfma_f32_32x32x16_bf16 v[34:49], v[110:113], v[98:101], v[34:49]
	v_mfma_f32_32x32x16_bf16 v[82:97], v[110:113], v[102:105], v[82:97]
	s_waitcnt lgkmcnt(0)
	v_mfma_f32_32x32x16_bf16 v[66:81], v[114:117], v[98:101], v[66:81]
	v_mfma_f32_32x32x16_bf16 v[50:65], v[114:117], v[102:105], v[50:65]
	v_mfma_f32_32x32x16_bf16 v[2:17], v[222:225], v[98:101], v[2:17]
	v_mfma_f32_32x32x16_bf16 v[18:33], v[222:225], v[102:105], v[18:33]

; #define LAS __attribute__((address_space(3)))
; __device__ __forceinline__ void attn_fast_x2(float mr1, f32x16& L1, f32x16& oa0, f32x16& oa1, float mr2, f32x16& L2, f32x16& ob0, f32x16& ob1, ...
;     f32x16 s1, s2;
; #pragma unroll
;     for (int i = 0; i < 16; ++i) { s1[i] = -mr1; s2[i] = -mr2; }
; #pragma unroll
;     for (int ks = 0; ks < 2; ++ks) { const bf16x8 a1 = *(const LAS bf16x8*)(Ks + (kr0 + r) * KP + 16 * ks + 8 * h), a2 = *(const LAS bf16x8*)(Ks + (kr0 + r) * KP + 32 + 16 * ks + 8 * h);
;         s1 = __builtin_amdgcn_mfma_f32_32x32x16_bf16(a1, qf1[ks], s1, 0, 0, 0); s2 = __builtin_amdgcn_mfma_f32_32x32x16_bf16(a2, qf2[ks], s2, 0, 0, 0); }
;     if (need_mask) {
; #pragma unroll
;         for (int i = 0; i < 16; ++i) { const bool ok = (key0 + rowi32(i, h)) <= qpos; s1[i] = ok ? s1[i] : NEG; s2[i] = ok ? s2[i] : NEG; }
;     }
;     float p1[16], p2[16];
; #pragma unroll
;     for (int i = 0; i < 16; ++i) { p1[i] = ex2(s1[i]); p2[i] = ex2(s2[i]); }
;     const u32x4 onesu = {0x3f803f80u, 0x3f803f80u, 0x3f803f80u, 0x3f803f80u}; const bf16x8 ones = __builtin_bit_cast(bf16x8, onesu);
; #pragma unroll
;     for (int s2i = 0; s2i < 2; ++s2i) {
;         const bf16x8 pb1 = pack8(p1[8 * s2i + 0], p1[8 * s2i + 1], p1[8 * s2i + 2], p1[8 * s2i + 3], p1[8 * s2i + 4], p1[8 * s2i + 5], p1[8 * s2i + 6], p1[8 * s2i + 7]);
;         const bf16x8 pb2 = pack8(p2[8 * s2i + 0], p2[8 * s2i + 1], p2[8 * s2i + 2], p2[8 * s2i + 3], p2[8 * s2i + 4], p2[8 * s2i + 5], p2[8 * s2i + 6], p2[8 * s2i + 7]);
;         const LAS bf16_t* vp = Vt + r * VP + kr0 + 16 * s2i + 4 * h;
;         const u32x2 a0l = *(const LAS u32x2*)vp, a0h = *(const LAS u32x2*)(vp + 8);
;         const u32x2 a1l = *(const LAS u32x2*)(vp + 32 * VP), a1h = *(const LAS u32x2*)(vp + 32 * VP + 8);
;         const u32x4 v0 = {a0l.x, a0l.y, a0h.x, a0h.y}, v1 = {a1l.x, a1l.y, a1h.x, a1h.y};
;         oa0 = __builtin_amdgcn_mfma_f32_32x32x16_bf16(__builtin_bit_cast(bf16x8, v0), pb1, oa0, 0, 0, 0);
;         ob0 = __builtin_amdgcn_mfma_f32_32x32x16_bf16(__builtin_bit_cast(bf16x8, v0), pb2, ob0, 0, 0, 0);
;         oa1 = __builtin_amdgcn_mfma_f32_32x32x16_bf16(__builtin_bit_cast(bf16x8, v1), pb1, oa1, 0, 0, 0);
;         ob1 = __builtin_amdgcn_mfma_f32_32x32x16_bf16(__builtin_bit_cast(bf16x8, v1), pb2, ob1, 0, 0, 0);
;         L1 = __builtin_amdgcn_mfma_f32_32x32x16_bf16(ones, pb1, L1, 0, 0, 0);
.Lda_fast:
	v_lshl_add_u32 v189, v248, 1, v181
	v_lshlrev_b32_e32 v99, 1, v248
	v_add3_u32 v99, s18, v240, v99
	ds_read_b128 v[100:103], v189
	ds_read_b128 v[104:107], v189 offset:32
	ds_read_b128 v[108:111], v189 offset:64
	ds_read_b128 v[112:115], v189 offset:96
	ds_read_b128 v[182:185], v99
	ds_read_b128 v[226:229], v99 offset:32
	ds_read_b128 v[242:245], v99 offset:64
	ds_read_b128 v[172:175], v99 offset:96
	v_lshl_add_u32 v98, v248, 1, v181
	v_add_u32_e32 v181, 0x3000, v98
	v_add_u32_e32 v98, 0x2000, v98
	s_waitcnt lgkmcnt(7)
	v_mfma_f32_32x32x16_bf16 v[116:131], v[100:103], v[152:155], v[206:221]
	s_waitcnt lgkmcnt(6)
	v_mfma_f32_32x32x16_bf16 v[116:131], v[104:107], v[156:159], v[116:131]
	s_waitcnt lgkmcnt(5)
	v_mfma_f32_32x32x16_bf16 v[132:147], v[108:111], v[160:163], v[190:205]
	s_waitcnt lgkmcnt(4)
	v_mfma_f32_32x32x16_bf16 v[132:147], v[112:115], v[148:151], v[132:147]
	ds_read_b128 v[100:103], v98 offset:1024
	ds_read_b128 v[104:107], v181 offset:1536
	ds_read_b128 v[108:111], v98 offset:1056
	ds_read_b128 v[112:115], v181 offset:1568
	s_nop 3
	v_exp_f32_e32 v116, v116
	v_exp_f32_e32 v117, v117
	v_exp_f32_e32 v118, v118
	v_exp_f32_e32 v119, v119
	v_exp_f32_e32 v120, v120
	v_exp_f32_e32 v121, v121
	v_exp_f32_e32 v122, v122
	v_exp_f32_e32 v123, v123
	v_cvt_pk_bf16_f32 v116, v116, v117
	v_cvt_pk_bf16_f32 v117, v118, v119
	v_cvt_pk_bf16_f32 v118, v120, v121
	v_cvt_pk_bf16_f32 v119, v122, v123
	s_waitcnt lgkmcnt(2)
	s_nop 0
	v_mfma_f32_32x32x16_bf16 v[34:49], v[100:103], v[116:119], v[34:49]
	v_exp_f32_e32 v124, v124
	v_exp_f32_e32 v125, v125
	v_exp_f32_e32 v126, v126
	v_mfma_f32_32x32x16_bf16 v[66:81], v[104:107], v[116:119], v[66:81]
	v_exp_f32_e32 v127, v127
	v_exp_f32_e32 v128, v128
	v_exp_f32_e32 v129, v129
	v_mfma_f32_32x32x16_bf16 v[2:17], v[222:225], v[116:119], v[2:17]
	v_exp_f32_e32 v130, v130
	v_exp_f32_e32 v131, v131
	v_cvt_pk_bf16_f32 v120, v124, v125
	v_cvt_pk_bf16_f32 v121, v126, v127
	v_cvt_pk_bf16_f32 v122, v128, v129
	v_cvt_pk_bf16_f32 v123, v130, v131
	s_waitcnt lgkmcnt(0)
	s_nop 0
	v_mfma_f32_32x32x16_bf16 v[34:49], v[108:111], v[120:123], v[34:49]
	v_exp_f32_e32 v132, v132
	v_exp_f32_e32 v133, v133
	v_exp_f32_e32 v134, v134
	v_mfma_f32_32x32x16_bf16 v[66:81], v[112:115], v[120:123], v[66:81]
	v_exp_f32_e32 v135, v135
	v_exp_f32_e32 v136, v136
	v_exp_f32_e32 v137, v137
	v_mfma_f32_32x32x16_bf16 v[2:17], v[222:225], v[120:123], v[2:17]
	v_exp_f32_e32 v138, v138
	v_exp_f32_e32 v139, v139
	v_cvt_pk_bf16_f32 v132, v132, v133
	v_cvt_pk_bf16_f32 v133, v134, v135
	v_mfma_f32_32x32x16_bf16 v[116:131], v[182:185], v[152:155], v[206:221]
	v_cvt_pk_bf16_f32 v134, v136, v137
	v_cvt_pk_bf16_f32 v135, v138, v139
	v_exp_f32_e32 v140, v140
	v_exp_f32_e32 v141, v141
	v_mfma_f32_32x32x16_bf16 v[116:131], v[226:229], v[156:159], v[116:131]
	v_exp_f32_e32 v142, v142
	v_exp_f32_e32 v143, v143
	v_exp_f32_e32 v144, v144
	ds_read_b128 v[182:185], v98 offset:1088
	ds_read_b128 v[226:229], v181 offset:1600
	v_mfma_f32_32x32x16_bf16 v[82:97], v[100:103], v[132:135], v[82:97]
	v_exp_f32_e32 v145, v145
	v_exp_f32_e32 v146, v146
	v_exp_f32_e32 v147, v147
	v_mfma_f32_32x32x16_bf16 v[50:65], v[104:107], v[132:135], v[50:65]
	v_cvt_pk_bf16_f32 v136, v140, v141
	v_cvt_pk_bf16_f32 v137, v142, v143
	v_cvt_pk_bf16_f32 v138, v144, v145
	v_cvt_pk_bf16_f32 v139, v146, v147
	ds_read_b128 v[100:103], v98 offset:1120
	ds_read_b128 v[104:107], v181 offset:1632
	v_mfma_f32_32x32x16_bf16 v[18:33], v[222:225], v[132:135], v[18:33]
	v_exp_f32_e32 v116, v116
	v_exp_f32_e32 v117, v117
	v_exp_f32_e32 v118, v118
	v_mfma_f32_32x32x16_bf16 v[82:97], v[108:111], v[136:139], v[82:97]
	v_exp_f32_e32 v119, v119
	v_exp_f32_e32 v120, v120
	v_exp_f32_e32 v121, v121
	v_mfma_f32_32x32x16_bf16 v[50:65], v[112:115], v[136:139], v[50:65]
	v_exp_f32_e32 v122, v122
	v_exp_f32_e32 v123, v123
	v_cvt_pk_bf16_f32 v116, v116, v117
	v_cvt_pk_bf16_f32 v117, v118, v119
	v_mfma_f32_32x32x16_bf16 v[18:33], v[222:225], v[136:139], v[18:33]
	v_cvt_pk_bf16_f32 v118, v120, v121
	v_cvt_pk_bf16_f32 v119, v122, v123
	v_exp_f32_e32 v124, v124
	v_exp_f32_e32 v125, v125
	v_mfma_f32_32x32x16_bf16 v[132:147], v[242:245], v[160:163], v[190:205]
	v_exp_f32_e32 v126, v126
	v_exp_f32_e32 v127, v127
	v_exp_f32_e32 v128, v128
	v_mfma_f32_32x32x16_bf16 v[132:147], v[172:175], v[148:151], v[132:147]
	v_exp_f32_e32 v129, v129
	v_exp_f32_e32 v130, v130
	v_exp_f32_e32 v131, v131
	s_waitcnt lgkmcnt(2)
	v_mfma_f32_32x32x16_bf16 v[34:49], v[182:185], v[116:119], v[34:49]
	v_cvt_pk_bf16_f32 v120, v124, v125
	v_cvt_pk_bf16_f32 v121, v126, v127
	v_cvt_pk_bf16_f32 v122, v128, v129
	v_cvt_pk_bf16_f32 v123, v130, v131
	v_mfma_f32_32x32x16_bf16 v[66:81], v[226:229], v[116:119], v[66:81]
	s_nop 1
	v_exp_f32_e32 v132, v132
	v_exp_f32_e32 v133, v133
	v_exp_f32_e32 v134, v134
	v_mfma_f32_32x32x16_bf16 v[2:17], v[222:225], v[116:119], v[2:17]
	v_exp_f32_e32 v135, v135
	v_exp_f32_e32 v136, v136
	v_exp_f32_e32 v137, v137
	s_waitcnt lgkmcnt(0)
	v_mfma_f32_32x32x16_bf16 v[34:49], v[100:103], v[120:123], v[34:49]
	v_exp_f32_e32 v138, v138
	v_exp_f32_e32 v139, v139
	v_cvt_pk_bf16_f32 v132, v132, v133
	v_cvt_pk_bf16_f32 v133, v134, v135
	v_mfma_f32_32x32x16_bf16 v[66:81], v[104:107], v[120:123], v[66:81]
	v_cvt_pk_bf16_f32 v134, v136, v137
	v_cvt_pk_bf16_f32 v135, v138, v139
	v_exp_f32_e32 v140, v140
	v_exp_f32_e32 v141, v141
	v_mfma_f32_32x32x16_bf16 v[2:17], v[222:225], v[120:123], v[2:17]
	v_exp_f32_e32 v142, v142
	v_exp_f32_e32 v143, v143
	v_exp_f32_e32 v144, v144
	v_mfma_f32_32x32x16_bf16 v[18:33], v[222:225], v[132:135], v[18:33]
	v_exp_f32_e32 v145, v145
	v_exp_f32_e32 v146, v146
	v_exp_f32_e32 v147, v147
	v_mfma_f32_32x32x16_bf16 v[82:97], v[182:185], v[132:135], v[82:97]
	v_cvt_pk_bf16_f32 v136, v140, v141
	v_cvt_pk_bf16_f32 v137, v142, v143
	v_cvt_pk_bf16_f32 v138, v144, v145
	v_cvt_pk_bf16_f32 v139, v146, v147
	v_mfma_f32_32x32x16_bf16 v[50:65], v[226:229], v[132:135], v[50:65]
	s_nop 0
	v_mfma_f32_32x32x16_bf16 v[18:33], v[222:225], v[136:139], v[18:33]
	v_mfma_f32_32x32x16_bf16 v[82:97], v[100:103], v[136:139], v[82:97]
	v_mfma_f32_32x32x16_bf16 v[50:65], v[104:107], v[136:139], v[50:65]
	s_xor_b32 s24, s20, 1
	s_mul_i32 s24, s24, 0x4800
	v_add3_u32 v189, s24, v249, v238
	s_waitcnt vmcnt(1)
	ds_write_b128 v189, v[168:171]
	v_lshl_add_u32 v189, v251, 1, s24
	s_waitcnt vmcnt(0)
	ds_write_b16 v189, v164 offset:9216
	ds_write_b16_d16_hi v189, v164 offset:9360
	ds_write_b16 v189, v165 offset:9504
	ds_write_b16_d16_hi v189, v165 offset:9648
	ds_write_b16 v189, v166 offset:9792
	ds_write_b16_d16_hi v189, v166 offset:9936
	ds_write_b16 v189, v167 offset:10080
	v_lshl_add_u32 v189, v239, 1, s24
	s_cmp_ge_u32 s21, s6
	ds_write_b16_d16_hi v189, v167 offset:9216
	s_cbranch_scc1 .Lda_fast_nofetch
	global_load_dwordx4 v[168:171], v[234:235], off
	global_load_dwordx4 v[164:167], v[236:237], off

; #define LAS __attribute__((address_space(3)))
; __device__ __forceinline__ float ex2(float x) { return __builtin_amdgcn_exp2f(x); }
; __device__ __forceinline__ void attn_fast_x2(float mr1, f32x16& L1, f32x16& oa0, f32x16& oa1, float mr2, f32x16& L2, f32x16& ob0, f32x16& ob1, ...
;     ...
;     float p1[16], p2[16];
; #pragma unroll
;     for (int i = 0; i < 16; ++i) { p1[i] = ex2(s1[i]); p2[i] = ex2(s2[i]); }
;     const u32x4 onesu = {0x3f803f80u, 0x3f803f80u, 0x3f803f80u, 0x3f803f80u}; const bf16x8 ones = __builtin_bit_cast(bf16x8, onesu);
; #pragma unroll
;     for (int s2i = 0; s2i < 2; ++s2i) {
;         const bf16x8 pb1 = pack8(p1[8 * s2i + 0], p1[8 * s2i + 1], p1[8 * s2i + 2], p1[8 * s2i + 3], p1[8 * s2i + 4], p1[8 * s2i + 5], p1[8 * s2i + 6], p1[8 * s2i + 7]);
;         const bf16x8 pb2 = pack8(p2[8 * s2i + 0], p2[8 * s2i + 1], p2[8 * s2i + 2], p2[8 * s2i + 3], p2[8 * s2i + 4], p2[8 * s2i + 5], p2[8 * s2i + 6], p2[8 * s2i + 7]);
;         const LAS bf16_t* vp = Vt + r * VP + kr0 + 16 * s2i + 4 * h;
;         const u32x2 a0l = *(const LAS u32x2*)vp, a0h = *(const LAS u32x2*)(vp + 8);
;         const u32x2 a1l = *(const LAS u32x2*)(vp + 32 * VP), a1h = *(const LAS u32x2*)(vp + 32 * VP + 8);
;         const u32x4 v0 = {a0l.x, a0l.y, a0h.x, a0h.y}, v1 = {a1l.x, a1l.y, a1h.x, a1h.y};
;         oa0 = __builtin_amdgcn_mfma_f32_32x32x16_bf16(__builtin_bit_cast(bf16x8, v0), pb1, oa0, 0, 0, 0);
;         ob0 = __builtin_amdgcn_mfma_f32_32x32x16_bf16(__builtin_bit_cast(bf16x8, v0), pb2, ob0, 0, 0, 0);
;         oa1 = __builtin_amdgcn_mfma_f32_32x32x16_bf16(__builtin_bit_cast(bf16x8, v1), pb1, oa1, 0, 0, 0);
;         ob1 = __builtin_amdgcn_mfma_f32_32x32x16_bf16(__builtin_bit_cast(bf16x8, v1), pb2, ob1, 0, 0, 0);
;         L1 = __builtin_amdgcn_mfma_f32_32x32x16_bf16(ones, pb1, L1, 0, 0, 0);
;         L2 = __builtin_amdgcn_mfma_f32_32x32x16_bf16(ones, pb2, L2, 0, 0, 0);
;     }
.LBB0_265:
	s_nop 4
	v_exp_f32_e32 v99, v116
	v_exp_f32_e32 v101, v117
	v_exp_f32_e32 v106, v120
	v_exp_f32_e32 v107, v121
	v_exp_f32_e32 v112, v122
	v_exp_f32_e32 v115, v123
	v_exp_f32_e32 v100, v132
	v_exp_f32_e32 v102, v133
	v_exp_f32_e32 v103, v118
	v_exp_f32_e32 v108, v134
	v_exp_f32_e32 v105, v119
	v_exp_f32_e32 v109, v135
	v_exp_f32_e32 v110, v136
	v_exp_f32_e32 v111, v137
	v_exp_f32_e32 v113, v138
	v_exp_f32_e32 v116, v139
	v_cvt_pk_bf16_f32 v104, v99, v101
	v_lshl_add_u32 v99, v248, 1, v181
	v_cvt_pk_bf16_f32 v106, v106, v107
	v_cvt_pk_bf16_f32 v107, v112, v115
	v_add_u32_e32 v112, 0x2000, v99
	v_add_u32_e32 v99, 0x3000, v99
	v_cvt_pk_bf16_f32 v105, v103, v105
	v_cvt_pk_bf16_f32 v100, v100, v102
	v_cvt_pk_bf16_f32 v101, v108, v109
	v_cvt_pk_bf16_f32 v102, v110, v111
	v_cvt_pk_bf16_f32 v103, v113, v116
	ds_read_b128 v[108:111], v112 offset:1024
	ds_read_b128 v[116:119], v112 offset:1056
	ds_read_b128 v[120:123], v99 offset:1536
	s_mov_b32 s30, s28
	s_mov_b32 s31, s28
	s_waitcnt lgkmcnt(2)
	v_mfma_f32_32x32x16_bf16 v[34:49], v[108:111], v[104:107], v[34:49]
	s_mov_b32 s29, s28
	v_exp_f32_e32 v124, v124
	v_exp_f32_e32 v132, v140
	v_exp_f32_e32 v125, v125
	v_exp_f32_e32 v133, v141
	v_exp_f32_e32 v126, v126
	v_exp_f32_e32 v134, v142
	v_mfma_f32_32x32x16_bf16 v[82:97], v[108:111], v[100:103], v[82:97]
	v_mov_b64_e32 v[110:111], s[30:31]
	v_mov_b64_e32 v[108:109], s[28:29]
	v_exp_f32_e32 v127, v127
	v_exp_f32_e32 v135, v143
	v_exp_f32_e32 v128, v128
	v_exp_f32_e32 v136, v144
	v_exp_f32_e32 v129, v129
	s_waitcnt lgkmcnt(0)
	v_mfma_f32_32x32x16_bf16 v[66:81], v[120:123], v[104:107], v[66:81]
	v_exp_f32_e32 v137, v145
	v_exp_f32_e32 v130, v130
	v_exp_f32_e32 v138, v146
	v_exp_f32_e32 v131, v131
	v_exp_f32_e32 v139, v147
	v_mfma_f32_32x32x16_bf16 v[50:65], v[120:123], v[100:103], v[50:65]
	ds_read_b128 v[120:123], v99 offset:1568
	v_mfma_f32_32x32x16_bf16 v[2:17], v[108:111], v[104:107], v[2:17]
	v_cvt_pk_bf16_f32 v104, v132, v133
	v_cvt_pk_bf16_f32 v105, v134, v135
	v_cvt_pk_bf16_f32 v106, v136, v137
	v_cvt_pk_bf16_f32 v107, v138, v139
	v_mfma_f32_32x32x16_bf16 v[18:33], v[108:111], v[100:103], v[18:33]
	v_cvt_pk_bf16_f32 v100, v124, v125
	v_cvt_pk_bf16_f32 v101, v126, v127
	v_cvt_pk_bf16_f32 v102, v128, v129
	v_cvt_pk_bf16_f32 v103, v130, v131
	s_nop 1
	v_mfma_f32_32x32x16_bf16 v[34:49], v[116:119], v[100:103], v[34:49]
	v_mfma_f32_32x32x16_bf16 v[82:97], v[116:119], v[104:107], v[82:97]
	s_waitcnt lgkmcnt(0)
	v_mfma_f32_32x32x16_bf16 v[66:81], v[120:123], v[100:103], v[66:81]
	v_mfma_f32_32x32x16_bf16 v[50:65], v[120:123], v[104:107], v[50:65]
	v_mfma_f32_32x32x16_bf16 v[2:17], v[108:111], v[100:103], v[2:17]
	v_mfma_f32_32x32x16_bf16 v[18:33], v[108:111], v[104:107], v[18:33]

; #define LAS __attribute__((address_space(3)))
; __device__ __forceinline__ float ex2(float x) { return __builtin_amdgcn_exp2f(x); }
; __device__ __forceinline__ void attn_fast_x2(float mr1, f32x16& L1, f32x16& oa0, f32x16& oa1, float mr2, f32x16& L2, f32x16& ob0, f32x16& ob1, ...
;     ...
;     float p1[16], p2[16];
; #pragma unroll
;     for (int i = 0; i < 16; ++i) { p1[i] = ex2(s1[i]); p2[i] = ex2(s2[i]); }
;     const u32x4 onesu = {0x3f803f80u, 0x3f803f80u, 0x3f803f80u, 0x3f803f80u}; const bf16x8 ones = __builtin_bit_cast(bf16x8, onesu);
; #pragma unroll
;     for (int s2i = 0; s2i < 2; ++s2i) {
;         const bf16x8 pb1 = pack8(p1[8 * s2i + 0], p1[8 * s2i + 1], p1[8 * s2i + 2], p1[8 * s2i + 3], p1[8 * s2i + 4], p1[8 * s2i + 5], p1[8 * s2i + 6], p1[8 * s2i + 7]);
;         const bf16x8 pb2 = pack8(p2[8 * s2i + 0], p2[8 * s2i + 1], p2[8 * s2i + 2], p2[8 * s2i + 3], p2[8 * s2i + 4], p2[8 * s2i + 5], p2[8 * s2i + 6], p2[8 * s2i + 7]);
;         const LAS bf16_t* vp = Vt + r * VP + kr0 + 16 * s2i + 4 * h;
;         const u32x2 a0l = *(const LAS u32x2*)vp, a0h = *(const LAS u32x2*)(vp + 8);
;         const u32x2 a1l = *(const LAS u32x2*)(vp + 32 * VP), a1h = *(const LAS u32x2*)(vp + 32 * VP + 8);
;         const u32x4 v0 = {a0l.x, a0l.y, a0h.x, a0h.y}, v1 = {a1l.x, a1l.y, a1h.x, a1h.y};
;         oa0 = __builtin_amdgcn_mfma_f32_32x32x16_bf16(__builtin_bit_cast(bf16x8, v0), pb1, oa0, 0, 0, 0);
;         ob0 = __builtin_amdgcn_mfma_f32_32x32x16_bf16(__builtin_bit_cast(bf16x8, v0), pb2, ob0, 0, 0, 0);
;         oa1 = __builtin_amdgcn_mfma_f32_32x32x16_bf16(__builtin_bit_cast(bf16x8, v1), pb1, oa1, 0, 0, 0);
;         ob1 = __builtin_amdgcn_mfma_f32_32x32x16_bf16(__builtin_bit_cast(bf16x8, v1), pb2, ob1, 0, 0, 0);
;         L1 = __builtin_amdgcn_mfma_f32_32x32x16_bf16(ones, pb1, L1, 0, 0, 0);
;         L2 = __builtin_amdgcn_mfma_f32_32x32x16_bf16(ones, pb2, L2, 0, 0, 0);
;     }
.LBB0_269:
	s_nop 7
	v_exp_f32_e32 v114, v114
	v_exp_f32_e32 v115, v115
	v_exp_f32_e32 v118, v118
	v_exp_f32_e32 v119, v119
	v_exp_f32_e32 v116, v116
	v_exp_f32_e32 v117, v117
	v_exp_f32_e32 v130, v102
	v_cvt_pk_bf16_f32 v102, v114, v115
	v_lshl_add_u32 v114, v248, 1, v181
	v_exp_f32_e32 v98, v98
	v_exp_f32_e32 v99, v99
	v_exp_f32_e32 v100, v100
	v_exp_f32_e32 v101, v101
	v_exp_f32_e32 v131, v103
	v_exp_f32_e32 v120, v120
	v_exp_f32_e32 v132, v104
	v_exp_f32_e32 v121, v121
	v_exp_f32_e32 v133, v105
	v_exp_f32_e32 v138, v110
	v_cvt_pk_bf16_f32 v104, v118, v119
	v_add_u32_e32 v110, 0x2000, v114
	v_add_u32_e32 v118, 0x3000, v114
	v_exp_f32_e32 v134, v106
	v_exp_f32_e32 v135, v107
	v_exp_f32_e32 v136, v108
	v_exp_f32_e32 v137, v109
	v_exp_f32_e32 v139, v111
	v_exp_f32_e32 v140, v112
	v_exp_f32_e32 v141, v113
	v_cvt_pk_bf16_f32 v103, v116, v117
	ds_read_b128 v[106:109], v110 offset:1088
	ds_read_b128 v[110:113], v110 offset:1120
	ds_read_b128 v[114:117], v118 offset:1600
	v_cvt_pk_bf16_f32 v105, v120, v121
	v_cvt_pk_bf16_f32 v98, v98, v99
	v_cvt_pk_bf16_f32 v99, v100, v101
	v_cvt_pk_bf16_f32 v100, v130, v131
	v_cvt_pk_bf16_f32 v101, v132, v133
	s_mov_b32 s30, s28
	s_mov_b32 s31, s28
	s_waitcnt lgkmcnt(2)
	v_mfma_f32_32x32x16_bf16 v[34:49], v[106:109], v[102:105], v[34:49]
	s_mov_b32 s29, s28
	v_exp_f32_e32 v122, v122
	v_exp_f32_e32 v123, v123
	v_exp_f32_e32 v124, v124
	v_exp_f32_e32 v125, v125
	v_exp_f32_e32 v126, v126
	v_exp_f32_e32 v127, v127
	v_mfma_f32_32x32x16_bf16 v[82:97], v[106:109], v[98:101], v[82:97]
	v_mov_b64_e32 v[108:109], s[30:31]
	v_mov_b64_e32 v[106:107], s[28:29]
	v_exp_f32_e32 v128, v128
	v_exp_f32_e32 v129, v129
	s_waitcnt lgkmcnt(0)
	v_mfma_f32_32x32x16_bf16 v[66:81], v[114:117], v[102:105], v[66:81]
	v_mfma_f32_32x32x16_bf16 v[50:65], v[114:117], v[98:101], v[50:65]
	ds_read_b128 v[114:117], v118 offset:1632
	v_mfma_f32_32x32x16_bf16 v[2:17], v[106:109], v[102:105], v[2:17]
	v_cvt_pk_bf16_f32 v102, v134, v135
	v_cvt_pk_bf16_f32 v103, v136, v137
	v_cvt_pk_bf16_f32 v104, v138, v139
	v_cvt_pk_bf16_f32 v105, v140, v141
	v_mfma_f32_32x32x16_bf16 v[18:33], v[106:109], v[98:101], v[18:33]
	v_cvt_pk_bf16_f32 v98, v122, v123
	v_cvt_pk_bf16_f32 v99, v124, v125
	v_cvt_pk_bf16_f32 v100, v126, v127
	v_cvt_pk_bf16_f32 v101, v128, v129
	s_nop 1
	v_mfma_f32_32x32x16_bf16 v[34:49], v[110:113], v[98:101], v[34:49]
	v_mfma_f32_32x32x16_bf16 v[82:97], v[110:113], v[102:105], v[82:97]
	s_waitcnt lgkmcnt(0)
	v_mfma_f32_32x32x16_bf16 v[66:81], v[114:117], v[98:101], v[66:81]
	v_mfma_f32_32x32x16_bf16 v[50:65], v[114:117], v[102:105], v[50:65]
	v_mfma_f32_32x32x16_bf16 v[2:17], v[106:109], v[98:101], v[2:17]
	v_mfma_f32_32x32x16_bf16 v[18:33], v[106:109], v[102:105], v[18:33]

; #define LAS __attribute__((address_space(3)))
; __device__ __forceinline__ unsigned pk4_fp8(float a, float b, float c, float d) { int w = __builtin_amdgcn_cvt_pk_fp8_f32(a, b, 0, false); w = __builtin_amdgcn_cvt_pk_fp8_f32(c, d, w, true); return (unsigned)w; }
; __device__ __forceinline__ u32x2 bf8_to_fp8(u32x4 v) {
;     u32x2 o;
;     o.x = pk4_fp8(__uint_as_float(v.x << 16), __uint_as_float(v.x & 0xffff0000u), __uint_as_float(v.y << 16), __uint_as_float(v.y & 0xffff0000u));
;     o.y = pk4_fp8(__uint_as_float(v.z << 16), __uint_as_float(v.z & 0xffff0000u), __uint_as_float(v.w << 16), __uint_as_float(v.w & 0xffff0000u));
;     return o;
; }
; __device__ __forceinline__ void phase_sel(const Params& p, LAS unsigned char* lds, const bf16_t* Z, const float* G, const unsigned char* K8, const unsigned char* V8T, const float* ACC, const int* IDX, bf16_t* Mixed, int tid, int wid, int lane) {
;     ...
;         long qf[2];
;         { const u32x2 qa = bf8_to_fp8(qr0), qb2 = bf8_to_fp8(qr1); qf[0] = mk64(qa.x, qa.y); qf[1] = mk64(qb2.x, qb2.y); }
;         const int nblk = __builtin_popcountll(__ballot(myidx >= 0));
;         const int head = g * 4 + (cc & 3);
;         const float gate_pre = G[row * 32 + 8 + head * 3 + 1];
;         LAS unsigned char* land = lds + 32768 + wid * 4096;
; #pragma unroll
;         for (int d = 0; d < 4; ++d) __builtin_amdgcn_global_load_lds((const unsigned*)(ACC + row * 512 + head * 64 + 16 * d + 4 * q4), (LAS unsigned*)(land + d * 1024), 16, 0, 0);
;         float m = NEG, l = 0.f; f32x4 o[4];
; #pragma unroll
;         for (int d = 0; d < 4; ++d) o[d] = (f32x4){0.f, 0.f, 0.f, 0.f};
.LBB0_646:
	s_waitcnt vmcnt(0)
	v_lshlrev_b32_e32 v0, 16, v110
	v_and_b32_e32 v110, 0xffff0000, v110
	v_cvt_pk_fp8_f32 v208, v0, v110
	v_lshlrev_b32_e32 v0, 16, v112
	v_and_b32_e32 v110, 0xffff0000, v112
	v_cvt_pk_fp8_f32 v209, v0, v110
	v_lshlrev_b32_e32 v0, 16, v113
	v_and_b32_e32 v110, 0xffff0000, v113
	v_cvt_pk_fp8_f32 v209, v0, v110 op_sel:[0,0,1]
	v_lshlrev_b32_e32 v0, 16, v98
	v_and_b32_e32 v98, 0xffff0000, v98
	v_cvt_pk_fp8_f32 v210, v0, v98
	v_lshlrev_b32_e32 v0, 16, v100
	v_and_b32_e32 v98, 0xffff0000, v100
	v_cvt_pk_fp8_f32 v211, v0, v98
	v_lshlrev_b32_e32 v140, 16, v111
	v_and_b32_e32 v111, 0xffff0000, v111
	v_lshlrev_b32_e32 v110, 16, v99
	v_and_b32_e32 v99, 0xffff0000, v99
	v_lshlrev_b32_e32 v0, 16, v101
	v_and_b32_e32 v98, 0xffff0000, v101
	v_cvt_pk_fp8_f32 v208, v140, v111 op_sel:[0,0,1]
	v_cvt_pk_fp8_f32 v210, v110, v99 op_sel:[0,0,1]
	v_cvt_pk_fp8_f32 v211, v0, v98 op_sel:[0,0,1]
	v_mov_b32_e32 v249, 0
	v_lshl_add_u64 v[212:213], v[138:139], 0, v[196:197]
	v_mov_b32_e32 v0, 0xf149f2ca
	s_mov_b32 s70, 0
	v_mov_b32_e32 v142, 0
	v_mov_b32_e32 v143, v249
	v_mov_b32_e32 v144, v249
	v_mov_b32_e32 v145, v249
	v_mov_b32_e32 v138, v249
	v_mov_b32_e32 v139, v249
	v_mov_b32_e32 v140, v249
	v_mov_b32_e32 v141, v249
	v_mov_b32_e32 v110, v249
	v_mov_b32_e32 v111, v249
	v_mov_b32_e32 v112, v249
	v_mov_b32_e32 v113, v249
	v_mov_b32_e32 v98, v249
	v_mov_b32_e32 v99, v249
	v_mov_b32_e32 v100, v249
	v_mov_b32_e32 v101, v249

; #define LAS __attribute__((address_space(3)))
; __device__ __forceinline__ float ex2(float x) { return __builtin_amdgcn_exp2f(x); }
; __device__ __forceinline__ unsigned pk4_fp8(float a, float b, float c, float d) { int w = __builtin_amdgcn_cvt_pk_fp8_f32(a, b, 0, false); w = __builtin_amdgcn_cvt_pk_fp8_f32(c, d, w, true); return (unsigned)w; }
; __device__ __forceinline__ void sel_load_any(SelBuf& B, const unsigned char* Kb, const unsigned char* Vb, const LAS unsigned char* fl, int jb, int cur, int cc, int q4) {
;     const int slot = (jb == 0) ? 0 : ((jb == cur - 1) ? 1 : ((jb == cur) ? 2 : -1));
;     if (slot < 0) { sel_load(B, Kb, Vb, jb, cc, q4); return; }
;     const LAS unsigned char* fk = fl + slot * 8192; const LAS unsigned char* fv = fk + 4096;
; #pragma unroll
;     for (int ht = 0; ht < 4; ++ht) { const int keyrow = 32 * (ht >> 1) + 8 * (cc >> 2) + (cc & 3) + 4 * (ht & 1); B.k[ht] = *(const LAS l64x2*)(fk + keyrow * 64 + q4 * 16); }
; __device__ __forceinline__ void sel_compute2(float& m, float& l, f32x4 (&o)[4], const long (&qf)[2], const SelBuf& A, const SelBuf& B, int kbA, int kbB, bool diagA, bool diagB, bool validB, int t, float c, int q4) {
;     ...
;     f32x2_t ps2 = {0.f, 0.f}; const f32x2_t c2 = {c, c}, mn2 = {mn, mn}, e8 = {8.f, 8.f};
; #pragma unroll
;     for (int ht = 0; ht < 8; ++ht)
; #pragma unroll
;         for (int e = 0; e < 4; e += 2) { f32x2_t tt = {s[ht][e], s[ht][e + 1]}; tt = (tt - mn2) * c2 + e8; s[ht][e] = ex2(tt.x); s[ht][e + 1] = ex2(tt.y); const f32x2_t pp = {s[ht][e], s[ht][e + 1]}; ps2 += pp; }
;     l = l * alpha + (ps2.x + ps2.y);
; #pragma unroll
;     for (int half = 0; half < 2; ++half) {
;         const long pa = mk64(pk4_fp8(s[2 * half][0], s[2 * half][1], s[2 * half][2], s[2 * half][3]), pk4_fp8(s[2 * half + 1][0], s[2 * half + 1][1], s[2 * half + 1][2], s[2 * half + 1][3]));
;         const long pbb = mk64(pk4_fp8(s[4 + 2 * half][0], s[4 + 2 * half][1], s[4 + 2 * half][2], s[4 + 2 * half][3]), pk4_fp8(s[4 + 2 * half + 1][0], s[4 + 2 * half + 1][1], s[4 + 2 * half + 1][2], s[4 + 2 * half + 1][3]));
; #pragma unroll
;         for (int d = 0; d < 4; ++d) {
;             o[d] = __builtin_amdgcn_mfma_f32_16x16x32_fp8_fp8(half ? A.v[d].y : A.v[d].x, pa, o[d], 0, 0, 0);
;             o[d] = __builtin_amdgcn_mfma_f32_16x16x32_fp8_fp8(half ? B.v[d].y : B.v[d].x, pbb, o[d], 0, 0, 0); }
;     }
.LBB0_716:
	v_mov_b64_e32 v[182:183], s[64:65]
	v_fma_f32 v183, -v214, s62, v182
	v_pk_fma_f32 v[170:171], v[170:171], s[62:63], v[182:183] op_sel:[0,0,1] op_sel_hi:[1,0,1]
	v_pk_fma_f32 v[166:167], v[166:167], s[62:63], v[182:183] op_sel:[0,0,1] op_sel_hi:[1,0,1]
	v_exp_f32_e32 v170, v170
	v_exp_f32_e32 v171, v171
	v_exp_f32_e32 v166, v166
	v_exp_f32_e32 v167, v167
	v_pk_fma_f32 v[172:173], v[172:173], s[62:63], v[182:183] op_sel:[0,0,1] op_sel_hi:[1,0,1]
	v_pk_fma_f32 v[168:169], v[168:169], s[62:63], v[182:183] op_sel:[0,0,1] op_sel_hi:[1,0,1]
	v_pk_fma_f32 v[162:163], v[162:163], s[62:63], v[182:183] op_sel:[0,0,1] op_sel_hi:[1,0,1]
	v_pk_fma_f32 v[164:165], v[164:165], s[62:63], v[182:183] op_sel:[0,0,1] op_sel_hi:[1,0,1]
	v_pk_fma_f32 v[174:175], v[174:175], s[62:63], v[182:183] op_sel:[0,0,1] op_sel_hi:[1,0,1]
	v_pk_fma_f32 v[176:177], v[176:177], s[62:63], v[182:183] op_sel:[0,0,1] op_sel_hi:[1,0,1]
	v_pk_fma_f32 v[150:151], v[150:151], s[62:63], v[182:183] op_sel:[0,0,1] op_sel_hi:[1,0,1]
	v_pk_fma_f32 v[152:153], v[152:153], s[62:63], v[182:183] op_sel:[0,0,1] op_sel_hi:[1,0,1]
	v_pk_fma_f32 v[146:147], v[146:147], s[62:63], v[182:183] op_sel:[0,0,1] op_sel_hi:[1,0,1]
	v_pk_fma_f32 v[148:149], v[148:149], s[62:63], v[182:183] op_sel:[0,0,1] op_sel_hi:[1,0,1]
	v_pk_fma_f32 v[154:155], v[154:155], s[62:63], v[182:183] op_sel:[0,0,1] op_sel_hi:[1,0,1]
	v_pk_fma_f32 v[156:157], v[156:157], s[62:63], v[182:183] op_sel:[0,0,1] op_sel_hi:[1,0,1]
	v_pk_fma_f32 v[158:159], v[158:159], s[62:63], v[182:183] op_sel:[0,0,1] op_sel_hi:[1,0,1]
	v_pk_fma_f32 v[160:161], v[160:161], s[62:63], v[182:183] op_sel:[0,0,1] op_sel_hi:[1,0,1]
	v_exp_f32_e32 v172, v172
	v_exp_f32_e32 v173, v173
	v_exp_f32_e32 v168, v168
	v_exp_f32_e32 v169, v169
	v_exp_f32_e32 v150, v150
	v_exp_f32_e32 v151, v151
	v_exp_f32_e32 v146, v146
	v_exp_f32_e32 v147, v147
	v_cvt_pk_fp8_f32 v182, v170, v171
	v_cvt_pk_fp8_f32 v183, v166, v167
	v_exp_f32_e32 v152, v152
	v_exp_f32_e32 v153, v153
	v_exp_f32_e32 v148, v148
	v_exp_f32_e32 v149, v149
	v_cvt_pk_fp8_f32 v182, v172, v173 op_sel:[0,0,1]
	v_cvt_pk_fp8_f32 v183, v168, v169 op_sel:[0,0,1]
	v_cvt_pk_fp8_f32 v184, v150, v151
	v_cvt_pk_fp8_f32 v185, v146, v147
	v_exp_f32_e32 v162, v162
	v_exp_f32_e32 v163, v163
	v_exp_f32_e32 v174, v174
	v_exp_f32_e32 v175, v175
	v_cvt_pk_fp8_f32 v184, v152, v153 op_sel:[0,0,1]
	v_cvt_pk_fp8_f32 v185, v148, v149 op_sel:[0,0,1]
	s_waitcnt vmcnt(3)
	v_mfma_f32_16x16x32_fp8_fp8 v[142:145], v[18:19], v[182:183], v[142:145]
	v_exp_f32_e32 v164, v164
	v_exp_f32_e32 v165, v165
	v_exp_f32_e32 v176, v176
	s_waitcnt vmcnt(2)
	v_mfma_f32_16x16x32_fp8_fp8 v[138:141], v[26:27], v[182:183], v[138:141]
	v_exp_f32_e32 v177, v177
	v_exp_f32_e32 v154, v154
	v_exp_f32_e32 v155, v155
	s_waitcnt vmcnt(1)
	v_mfma_f32_16x16x32_fp8_fp8 v[110:113], v[30:31], v[182:183], v[110:113]
	v_exp_f32_e32 v158, v158
	v_exp_f32_e32 v159, v159
	v_exp_f32_e32 v156, v156
	s_waitcnt vmcnt(0)
	v_mfma_f32_16x16x32_fp8_fp8 v[98:101], v[22:23], v[182:183], v[98:101]
	v_cvt_pk_fp8_f32 v182, v162, v163
	v_cvt_pk_fp8_f32 v183, v174, v175
	v_mfma_f32_16x16x32_fp8_fp8 v[142:145], v[66:67], v[184:185], v[142:145]
	v_exp_f32_e32 v157, v157
	v_exp_f32_e32 v160, v160
	v_exp_f32_e32 v161, v161
	v_mfma_f32_16x16x32_fp8_fp8 v[138:141], v[78:79], v[184:185], v[138:141]
	v_cvt_pk_fp8_f32 v182, v164, v165 op_sel:[0,0,1]
	v_cvt_pk_fp8_f32 v183, v176, v177 op_sel:[0,0,1]
	s_add_i32 s71, s70, 4
	v_mfma_f32_16x16x32_fp8_fp8 v[110:113], v[90:91], v[184:185], v[110:113]
	s_cmp_ge_u32 s71, s26
	s_cselect_b64 s[16:17], -1, 0
	s_and_b64 vcc, exec, s[16:17]
	v_mfma_f32_16x16x32_fp8_fp8 v[98:101], v[86:87], v[184:185], v[98:101]
	v_cvt_pk_fp8_f32 v184, v154, v155
	v_cvt_pk_fp8_f32 v185, v158, v159
	v_mfma_f32_16x16x32_fp8_fp8 v[142:145], v[20:21], v[182:183], v[142:145]
	v_cvt_pk_fp8_f32 v184, v156, v157 op_sel:[0,0,1]
	v_cvt_pk_fp8_f32 v185, v160, v161 op_sel:[0,0,1]
	v_mfma_f32_16x16x32_fp8_fp8 v[138:141], v[28:29], v[182:183], v[138:141]
	v_mfma_f32_16x16x32_fp8_fp8 v[110:113], v[32:33], v[182:183], v[110:113]
	v_mfma_f32_16x16x32_fp8_fp8 v[98:101], v[24:25], v[182:183], v[98:101]
	v_mfma_f32_16x16x32_fp8_fp8 v[142:145], v[68:69], v[184:185], v[142:145]
	v_mfma_f32_16x16x32_fp8_fp8 v[138:141], v[80:81], v[184:185], v[138:141]
	v_mfma_f32_16x16x32_fp8_fp8 v[110:113], v[92:93], v[184:185], v[110:113]
	v_mfma_f32_16x16x32_fp8_fp8 v[98:101], v[88:89], v[184:185], v[98:101]
	s_cbranch_vccnz .LBB0_726
	v_and_or_b32 v2, s71, 60, v181
	v_lshlrev_b32_e32 v2, 2, v2
	ds_bpermute_b32 v198, v2, v246
	s_add_i32 s2, s70, 5
	s_min_i32 s2, s2, s69
	v_and_or_b32 v2, s2, 63, v181
	v_lshlrev_b32_e32 v2, 2, v2
	ds_bpermute_b32 v202, v2, v246
	s_waitcnt lgkmcnt(1)
	v_cmp_eq_u32_e32 vcc, s51, v198
	s_nop 1
	v_cndmask_b32_e64 v2, -1, 2, vcc
	v_cmp_ne_u32_e32 vcc, s68, v198
	s_nop 1
	v_cndmask_b32_e32 v2, 1, v2, vcc
	v_cmp_ne_u32_e32 vcc, 0, v198
	s_nop 1
	v_cndmask_b32_e32 v34, 0, v2, vcc
	v_cmp_lt_i32_e32 vcc, -1, v34
	s_and_saveexec_b64 s[2:3], vcc
	s_xor_b64 s[2:3], exec, s[2:3]
	s_cbranch_execz .LBB0_719
	v_lshlrev_b32_e32 v2, 13, v34
	v_add3_u32 v18, 0, v2, v194
	v_add_u32_e32 v14, v18, v217
	v_add_u32_e32 v22, v18, v196
	ds_read_b128 v[2:5], v14
	ds_read_b128 v[6:9], v14 offset:256
	ds_read_b128 v[10:13], v14 offset:2048
	ds_read_b128 v[14:17], v14 offset:2304
	ds_read_b128 v[18:21], v22 offset:4096
	ds_read_b128 v[26:29], v22 offset:5120
	ds_read_b128 v[30:33], v22 offset:6144
	ds_read_b128 v[22:25], v22 offset:7168

; __device__ __forceinline__ float ex2(float x) { return __builtin_amdgcn_exp2f(x); }
; __device__ __forceinline__ unsigned pk4_fp8(float a, float b, float c, float d) { int w = __builtin_amdgcn_cvt_pk_fp8_f32(a, b, 0, false); w = __builtin_amdgcn_cvt_pk_fp8_f32(c, d, w, true); return (unsigned)w; }
; #define SEL_IDX(i) __shfl(myidx, (i) < last ? (i) : last)
; __device__ __forceinline__ void sel_compute2(float& m, float& l, f32x4 (&o)[4], const long (&qf)[2], const SelBuf& A, const SelBuf& B, int kbA, int kbB, bool diagA, bool diagB, bool validB, int t, float c, int q4) {
;     ...
;     f32x2_t ps2 = {0.f, 0.f}; const f32x2_t c2 = {c, c}, mn2 = {mn, mn}, e8 = {8.f, 8.f};
; #pragma unroll
;     for (int ht = 0; ht < 8; ++ht)
; #pragma unroll
;         for (int e = 0; e < 4; e += 2) { f32x2_t tt = {s[ht][e], s[ht][e + 1]}; tt = (tt - mn2) * c2 + e8; s[ht][e] = ex2(tt.x); s[ht][e + 1] = ex2(tt.y); const f32x2_t pp = {s[ht][e], s[ht][e + 1]}; ps2 += pp; }
;     l = l * alpha + (ps2.x + ps2.y);
; #pragma unroll
;     for (int half = 0; half < 2; ++half) {
;         const long pa = mk64(pk4_fp8(s[2 * half][0], s[2 * half][1], s[2 * half][2], s[2 * half][3]), pk4_fp8(s[2 * half + 1][0], s[2 * half + 1][1], s[2 * half + 1][2], s[2 * half + 1][3]));
;         const long pbb = mk64(pk4_fp8(s[4 + 2 * half][0], s[4 + 2 * half][1], s[4 + 2 * half][2], s[4 + 2 * half][3]), pk4_fp8(s[4 + 2 * half + 1][0], s[4 + 2 * half + 1][1], s[4 + 2 * half + 1][2], s[4 + 2 * half + 1][3]));
; #pragma unroll
;         for (int d = 0; d < 4; ++d) {
;             o[d] = __builtin_amdgcn_mfma_f32_16x16x32_fp8_fp8(half ? A.v[d].y : A.v[d].x, pa, o[d], 0, 0, 0);
;             o[d] = __builtin_amdgcn_mfma_f32_16x16x32_fp8_fp8(half ? B.v[d].y : B.v[d].x, pbb, o[d], 0, 0, 0); }
;     }
; __device__ __forceinline__ void phase_sel(const Params& p, LAS unsigned char* lds, const bf16_t* Z, const float* G, const unsigned char* K8, const unsigned char* V8T, const float* ACC, const int* IDX, bf16_t* Mixed, int tid, int wid, int lane) {
;     ...
;             if (k + 2 < nblk) sel_compute2(m, l, o, qf, b2, b3, j2 * 64, j3 * 64, j2 == cur, j3 == cur, k + 3 < nblk, t, c, q4);
;             if (k + 6 < nblk) { j2 = SEL_IDX(k + 6); j3 = SEL_IDX(k + 7); sel_load_any(b2, Kb, Vb, lds, j2, cur, cc, q4); sel_load_any(b3, Kb, Vb, lds, j3, cur, cc, q4); }
.LBB0_797:
	v_mov_b64_e32 v[182:183], s[64:65]
	v_fma_f32 v183, -v0, s62, v182
	v_pk_fma_f32 v[174:175], v[174:175], s[62:63], v[182:183] op_sel:[0,0,1] op_sel_hi:[1,0,1]
	v_exp_f32_e32 v214, v174
	v_exp_f32_e32 v215, v175
	v_pk_fma_f32 v[170:171], v[170:171], s[62:63], v[182:183] op_sel:[0,0,1] op_sel_hi:[1,0,1]
	v_pk_fma_f32 v[174:175], v[176:177], s[62:63], v[182:183] op_sel:[0,0,1] op_sel_hi:[1,0,1]
	v_exp_f32_e32 v174, v174
	v_exp_f32_e32 v175, v175
	v_exp_f32_e32 v176, v170
	v_exp_f32_e32 v177, v171
	v_pk_fma_f32 v[172:173], v[172:173], s[62:63], v[182:183] op_sel:[0,0,1] op_sel_hi:[1,0,1]
	v_exp_f32_e32 v172, v172
	v_exp_f32_e32 v173, v173
	v_pk_fma_f32 v[166:167], v[166:167], s[62:63], v[182:183] op_sel:[0,0,1] op_sel_hi:[1,0,1]
	v_pk_add_f32 v[184:185], v[214:215], 0 op_sel_hi:[1,0]
	v_exp_f32_e32 v166, v166
	v_exp_f32_e32 v167, v167
	v_pk_fma_f32 v[168:169], v[168:169], s[62:63], v[182:183] op_sel:[0,0,1] op_sel_hi:[1,0,1]
	v_pk_add_f32 v[184:185], v[174:175], v[184:185]
	v_exp_f32_e32 v168, v168
	v_exp_f32_e32 v169, v169
	v_pk_add_f32 v[170:171], v[176:177], v[184:185]
	v_pk_add_f32 v[170:171], v[172:173], v[170:171]
	v_pk_fma_f32 v[162:163], v[162:163], s[62:63], v[182:183] op_sel:[0,0,1] op_sel_hi:[1,0,1]
	v_pk_add_f32 v[170:171], v[166:167], v[170:171]
	v_pk_add_f32 v[184:185], v[168:169], v[170:171]
	v_exp_f32_e32 v170, v162
	v_exp_f32_e32 v171, v163
	v_pk_fma_f32 v[154:155], v[154:155], s[62:63], v[182:183] op_sel:[0,0,1] op_sel_hi:[1,0,1]
	v_pk_fma_f32 v[162:163], v[164:165], s[62:63], v[182:183] op_sel:[0,0,1] op_sel_hi:[1,0,1]
	v_exp_f32_e32 v162, v162
	v_exp_f32_e32 v163, v163
	v_exp_f32_e32 v154, v154
	v_exp_f32_e32 v155, v155
	v_pk_fma_f32 v[156:157], v[156:157], s[62:63], v[182:183] op_sel:[0,0,1] op_sel_hi:[1,0,1]
	v_pk_add_f32 v[184:185], v[170:171], v[184:185]
	v_exp_f32_e32 v156, v156
	v_exp_f32_e32 v157, v157
	v_pk_fma_f32 v[146:147], v[146:147], s[62:63], v[182:183] op_sel:[0,0,1] op_sel_hi:[1,0,1]
	v_pk_add_f32 v[164:165], v[162:163], v[184:185]
	v_exp_f32_e32 v184, v146
	v_exp_f32_e32 v185, v147
	v_pk_add_f32 v[164:165], v[154:155], v[164:165]
	v_pk_add_f32 v[164:165], v[156:157], v[164:165]
	v_pk_fma_f32 v[148:149], v[148:149], s[62:63], v[182:183] op_sel:[0,0,1] op_sel_hi:[1,0,1]
	v_pk_add_f32 v[146:147], v[184:185], v[164:165]
	v_exp_f32_e32 v164, v148
	v_exp_f32_e32 v165, v149
	s_nop 0
	v_pk_add_f32 v[148:149], v[164:165], v[146:147]
	v_pk_fma_f32 v[146:147], v[150:151], s[62:63], v[182:183] op_sel:[0,0,1] op_sel_hi:[1,0,1]
	v_pk_fma_f32 v[150:151], v[152:153], s[62:63], v[182:183] op_sel:[0,0,1] op_sel_hi:[1,0,1]
	v_exp_f32_e32 v146, v146
	v_exp_f32_e32 v147, v147
	v_exp_f32_e32 v150, v150
	v_exp_f32_e32 v151, v151
	v_pk_add_f32 v[148:149], v[146:147], v[148:149]
	s_nop 0
	v_pk_add_f32 v[152:153], v[150:151], v[148:149]
	s_nop 0
	v_pk_fma_f32 v[148:149], v[158:159], s[62:63], v[182:183] op_sel:[0,0,1] op_sel_hi:[1,0,1]
	s_nop 0
	v_exp_f32_e32 v148, v148
	v_exp_f32_e32 v149, v149
	s_nop 0
	v_pk_add_f32 v[158:159], v[148:149], v[152:153]
	v_pk_fma_f32 v[152:153], v[160:161], s[62:63], v[182:183] op_sel:[0,0,1] op_sel_hi:[1,0,1]
	v_exp_f32_e32 v152, v152
	v_exp_f32_e32 v153, v153
	v_cvt_pk_fp8_f32 v160, v154, v155
	v_cvt_pk_fp8_f32 v161, v184, v185
	v_pk_add_f32 v[158:159], v[152:153], v[158:159]
	v_add_f32_e32 v249, v158, v159
	v_cvt_pk_fp8_f32 v158, v214, v215
	v_cvt_pk_fp8_f32 v159, v176, v177
	v_cvt_pk_fp8_f32 v160, v156, v157 op_sel:[0,0,1]
	v_cvt_pk_fp8_f32 v161, v164, v165 op_sel:[0,0,1]
	v_cvt_pk_fp8_f32 v158, v174, v175 op_sel:[0,0,1]
	v_cvt_pk_fp8_f32 v159, v172, v173 op_sel:[0,0,1]
	v_cvt_pk_fp8_f32 v154, v166, v167
	v_cvt_pk_fp8_f32 v155, v170, v171
	v_mfma_f32_16x16x32_fp8_fp8 v[142:145], v[70:71], v[158:159], v[142:145]
	v_cvt_pk_fp8_f32 v154, v168, v169 op_sel:[0,0,1]
	v_mfma_f32_16x16x32_fp8_fp8 v[138:141], v[82:83], v[158:159], v[138:141]
	v_cvt_pk_fp8_f32 v155, v162, v163 op_sel:[0,0,1]
	v_cvt_pk_fp8_f32 v156, v146, v147
	v_cvt_pk_fp8_f32 v157, v148, v149
	v_mfma_f32_16x16x32_fp8_fp8 v[110:113], v[94:95], v[158:159], v[110:113]
	v_fmac_f32_e32 v249, v199, v216
	v_cvt_pk_fp8_f32 v156, v150, v151 op_sel:[0,0,1]
	v_cvt_pk_fp8_f32 v157, v152, v153 op_sel:[0,0,1]
	v_mfma_f32_16x16x32_fp8_fp8 v[98:101], v[74:75], v[158:159], v[98:101]
	v_mfma_f32_16x16x32_fp8_fp8 v[142:145], v[122:123], v[160:161], v[142:145]
	v_mfma_f32_16x16x32_fp8_fp8 v[138:141], v[126:127], v[160:161], v[138:141]
	v_mfma_f32_16x16x32_fp8_fp8 v[110:113], v[134:135], v[160:161], v[110:113]
	v_mfma_f32_16x16x32_fp8_fp8 v[98:101], v[130:131], v[160:161], v[98:101]
	v_mfma_f32_16x16x32_fp8_fp8 v[142:145], v[72:73], v[154:155], v[142:145]
	v_mfma_f32_16x16x32_fp8_fp8 v[138:141], v[84:85], v[154:155], v[138:141]
	v_mfma_f32_16x16x32_fp8_fp8 v[110:113], v[96:97], v[154:155], v[110:113]
	v_mfma_f32_16x16x32_fp8_fp8 v[98:101], v[76:77], v[154:155], v[98:101]
	v_mfma_f32_16x16x32_fp8_fp8 v[142:145], v[124:125], v[156:157], v[142:145]
	v_mfma_f32_16x16x32_fp8_fp8 v[138:141], v[128:129], v[156:157], v[138:141]
	v_mfma_f32_16x16x32_fp8_fp8 v[110:113], v[136:137], v[156:157], v[110:113]
	v_mfma_f32_16x16x32_fp8_fp8 v[98:101], v[132:133], v[156:157], v[98:101]
	s_add_i32 s2, s70, 6
	s_cmp_ge_u32 s2, s26
	s_cbranch_scc1 .LBB0_807
